# v071 with inverted scan priorities: producer waves at priority 3 during prep/write-out, consumer waves at 0
# baseline (speedup 1.0000x reference)
.LBB0_252:
	s_cmpk_gt_i32 s37, 0xff
	s_cselect_b64 s[78:79], -1, 0
	s_add_i32 s16, s46, 32
	s_cmpk_gt_i32 s46, 0x7ef
	s_cselect_b64 s[76:77], -1, 0
	s_and_b64 s[12:13], s[76:77], exec
	s_cselect_b32 s18, 0, s16
	s_cselect_b32 s19, s94, 0
	s_cmpk_lt_i32 s37, 0x100
	s_cselect_b64 s[12:13], -1, 0
	s_and_b64 s[16:17], s[12:13], exec
	s_cselect_b32 s24, s19, s91
	s_mov_b32 s4, s46
	s_mov_b32 s70, s37
	s_cselect_b32 s46, s18, 0
	s_add_i32 s37, s24, s37
	s_and_saveexec_b64 s[16:17], s[2:3]
	s_xor_b64 s[80:81], exec, s[16:17]
	s_cbranch_execz .LBB0_274
	s_setprio 3
	s_cmpk_gt_i32 s37, 0x10ff
	s_cbranch_scc1 .LBB0_265
	s_cmpk_lt_i32 s37, 0x100
	s_cselect_b64 vcc, -1, 0
	v_cndmask_b32_e64 v32, v232, 0, vcc
	v_add_u32_e32 v32, s37, v32
	s_movk_i32 s16, 0x1100
	v_cmp_gt_i32_e64 s[16:17], s16, v32
	s_and_saveexec_b64 s[84:85], s[16:17]
	s_cbranch_execz .LBB0_264
	s_movk_i32 s16, 0xff
	v_cmp_lt_i32_e64 s[16:17], s16, v32
	s_and_saveexec_b64 s[18:19], s[16:17]
	s_xor_b64 s[16:17], exec, s[18:19]
	v_add_u32_e32 v33, 0xffffff00, v32
	v_lshrrev_b32_e32 v33, 2, v33
	v_and_b32_e32 v33, 0x3ffffff8, v33
	v_add_u32_e32 v33, 0x4080, v33
	s_or_saveexec_b64 s[16:17], s[16:17]
	v_mov_b32_e32 v34, 8
	s_xor_b64 exec, exec, s[16:17]
	v_ashrrev_i32_e32 v33, 5, v32
	v_mov_b32_e32 v34, 0x810
	v_mul_lo_u32 v33, v33, v34
	s_or_b64 exec, exec, s[16:17]
	v_add_u32_e32 v35, s46, v189
	v_cndmask_b32_e32 v35, v195, v35, vcc
	v_cmp_lt_i32_e32 vcc, v35, v34
	s_and_b64 exec, exec, vcc
	s_cbranch_execz .LBB0_264
	v_add_u32_e32 v56, v33, v35
	v_ashrrev_i32_e32 v57, 31, v56
	v_bfe_u32 v72, v32, 1, 4
	v_lshlrev_b64 v[44:45], 11, v[56:57]
	v_and_b32_e32 v86, 1, v32
	v_lshl_add_u64 v[44:45], s[20:21], 0, v[44:45]
	v_lshlrev_b32_e32 v176, 7, v72
	s_load_dwordx4 s[16:19], s[48:49], 0xa8
	v_lshlrev_b64 v[32:33], 10, v[56:57]
	v_lshlrev_b32_e32 v73, 6, v72
	v_lshl_add_u64 v[44:45], v[44:45], 0, v[176:177]
	v_lshlrev_b32_e32 v176, 6, v86
	v_or_b32_e32 v32, v32, v73
	v_lshl_add_u64 v[44:45], v[44:45], 0, v[176:177]
	v_lshlrev_b32_e32 v176, 1, v188
	v_or_b32_e32 v32, v32, v190
	v_lshl_add_u64 v[44:45], v[44:45], 0, v[176:177]
	v_lshlrev_b64 v[40:41], 1, v[32:33]
	global_load_dwordx2 v[54:55], v[44:45], off
	v_lshlrev_b32_e32 v44, 8, v72
	v_mov_b32_e32 v45, v177
	v_lshl_add_u64 v[32:33], s[64:65], 0, v[40:41]
	v_lshl_add_u64 v[42:43], s[68:69], 0, v[40:41]
	s_waitcnt lgkmcnt(0)
	v_lshl_add_u64 v[58:59], s[16:17], 0, v[44:45]
	v_lshlrev_b32_e32 v176, 2, v190
	global_load_dwordx4 v[46:49], v[32:33], off
	global_load_dwordx4 v[50:53], v[42:43], off
	v_lshl_add_u64 v[32:33], s[62:63], 0, v[40:41]
	v_lshl_add_u64 v[40:41], s[66:67], 0, v[40:41]
	v_lshl_add_u64 v[58:59], v[58:59], 0, v[176:177]
	v_lshl_add_u64 v[44:45], s[18:19], 0, v[44:45]
	global_load_dwordx4 v[32:35], v[32:33], off
	v_lshl_add_u64 v[44:45], v[44:45], 0, v[176:177]
	global_load_dwordx4 v[40:43], v[40:41], off
	s_nop 0
	global_load_dwordx4 v[68:71], v[58:59], off offset:16
	global_load_dwordx4 v[62:65], v[58:59], off
	global_load_dwordx4 v[74:77], v[44:45], off offset:16
	global_load_dwordx4 v[78:81], v[44:45], off
	v_cmp_eq_u32_e32 vcc, 0, v86
	s_waitcnt vmcnt(7)
	v_lshlrev_b32_e32 v44, 16, v46
	v_and_b32_e32 v45, 0xffff0000, v46
	s_waitcnt vmcnt(6)
	v_lshlrev_b32_e32 v58, 16, v50
	v_and_b32_e32 v59, 0xffff0000, v50
	v_lshlrev_b32_e32 v46, 16, v47
	v_and_b32_e32 v47, 0xffff0000, v47
	s_waitcnt vmcnt(5)
	v_lshlrev_b32_e32 v36, 16, v32
	v_and_b32_e32 v37, 0xffff0000, v32
	v_lshlrev_b32_e32 v38, 16, v33
	s_waitcnt vmcnt(2)
	v_pk_mul_f32 v[60:61], v[62:63], v[44:45]
	v_pk_add_f32 v[62:63], v[58:59], -1.0 op_sel_hi:[1,0]
	v_pk_mul_f32 v[66:67], v[64:65], v[46:47]
	s_waitcnt vmcnt(0)
	v_pk_fma_f32 v[62:63], v[62:63], v[78:79], 1.0 op_sel_hi:[1,1,0]
	v_lshlrev_b32_e32 v64, 16, v52
	v_pk_mul_f32 v[44:45], v[62:63], v[44:45]
	v_lshlrev_b32_e32 v62, 16, v51
	v_and_b32_e32 v63, 0xffff0000, v51
	v_pk_add_f32 v[50:51], v[62:63], -1.0 op_sel_hi:[1,0]
	v_and_b32_e32 v65, 0xffff0000, v52
	v_pk_fma_f32 v[50:51], v[50:51], v[80:81], 1.0 op_sel_hi:[1,1,0]
	v_pk_add_f32 v[84:85], v[64:65], -1.0 op_sel_hi:[1,0]
	v_pk_mul_f32 v[82:83], v[60:61], v[60:61]
	v_pk_mul_f32 v[46:47], v[50:51], v[46:47]
	v_lshlrev_b32_e32 v50, 16, v48
	v_and_b32_e32 v51, 0xffff0000, v48
	v_pk_fma_f32 v[74:75], v[84:85], v[74:75], 1.0 op_sel_hi:[1,1,0]
	v_pk_mul_f32 v[78:79], v[66:67], v[66:67]
	v_pk_mul_f32 v[68:69], v[68:69], v[50:51]
	v_pk_mul_f32 v[50:51], v[74:75], v[50:51]
	v_add_f32_e32 v74, v82, v83
	v_add_f32_e32 v74, v78, v74
	v_pk_mul_f32 v[80:81], v[68:69], v[68:69]
	v_lshlrev_b32_e32 v84, 16, v49
	v_and_b32_e32 v85, 0xffff0000, v49
	v_add_f32_e32 v74, v79, v74
	v_pk_mul_f32 v[70:71], v[70:71], v[84:85]
	v_add_f32_e32 v74, v80, v74
	v_lshlrev_b32_e32 v48, 16, v53
	v_and_b32_e32 v49, 0xffff0000, v53
	v_pk_mul_f32 v[52:53], v[70:71], v[70:71]
	v_add_f32_e32 v74, v81, v74
	v_add_f32_e32 v52, v52, v74
	v_add_f32_e32 v52, v53, v52
	v_and_b32_e32 v39, 0xffff0000, v33
	v_lshlrev_b32_e32 v32, 16, v34
	v_add_f32_dpp v52, v52, v52 quad_perm:[1,0,3,2] row_mask:0xf bank_mask:0xf bound_ctrl:1
	v_and_b32_e32 v33, 0xffff0000, v34
	v_lshlrev_b32_e32 v34, 16, v35
	v_add_f32_dpp v74, v52, v52 quad_perm:[2,3,0,1] row_mask:0xf bank_mask:0xf bound_ctrl:1
	ds_bpermute_b32 v75, v221, v74
	v_pk_add_f32 v[52:53], v[48:49], -1.0 op_sel_hi:[1,0]
	v_and_b32_e32 v35, 0xffff0000, v35
	v_pk_fma_f32 v[52:53], v[52:53], v[76:77], 1.0 op_sel_hi:[1,1,0]
	s_nop 0
	v_pk_mul_f32 v[52:53], v[52:53], v[84:85]
	s_and_saveexec_b64 s[16:17], vcc
	s_cbranch_execz .LBB0_263
	s_load_dwordx2 s[18:19], s[48:49], 0xb8
	v_lshlrev_b32_e32 v76, 2, v73
	v_mov_b32_e32 v77, v177
	v_mul_f32_e32 v73, v44, v36
	s_waitcnt lgkmcnt(0)
	v_lshl_add_u64 v[76:77], s[18:19], 0, v[76:77]
	v_lshl_add_u64 v[80:81], v[76:77], 0, v[176:177]
	global_load_dwordx4 v[76:79], v[80:81], off offset:16
	s_nop 0
	global_load_dwordx4 v[80:83], v[80:81], off
	v_readlane_b32 s18, v254, 4
	v_readlane_b32 s19, v254, 5
	s_waitcnt vmcnt(0)
	v_fma_f32 v73, v73, v80, 0
	v_mul_f32_e32 v80, v45, v37
	v_fmac_f32_e32 v73, v80, v81
	v_mul_f32_e32 v80, v46, v38
	v_fmac_f32_e32 v73, v80, v82
	v_mul_f32_e32 v80, v47, v39
	v_fmac_f32_e32 v73, v80, v83
	v_mul_f32_e32 v80, v50, v32
	v_fmac_f32_e32 v73, v80, v76
	v_mul_f32_e32 v76, v51, v33
	v_fmac_f32_e32 v73, v76, v77
	v_mul_f32_e32 v76, v52, v34
	v_fmac_f32_e32 v73, v76, v78
	v_mul_f32_e32 v76, v53, v35
	v_fmac_f32_e32 v73, v76, v79
	s_nop 1
	v_add_f32_dpp v73, v73, v73 quad_perm:[1,0,3,2] row_mask:0xf bank_mask:0xf bound_ctrl:1
	s_nop 1
	v_add_f32_dpp v73, v73, v73 quad_perm:[2,3,0,1] row_mask:0xf bank_mask:0xf bound_ctrl:1
	ds_bpermute_b32 v76, v221, v73
	s_and_b64 exec, exec, s[18:19]
	s_cbranch_execz .LBB0_263
	v_lshlrev_b64 v[56:57], 6, v[56:57]
	v_lshl_add_u64 v[56:57], s[88:89], 0, v[56:57]
	v_lshlrev_b32_e32 v176, 2, v72
	s_waitcnt lgkmcnt(0)
	v_add_f32_e32 v73, v73, v76
	v_lshl_add_u64 v[56:57], v[56:57], 0, v[176:177]
	global_store_dword v[56:57], v73, off

.LBB0_274:
	s_setprio 0
	s_andn2_saveexec_b64 s[16:17], s[80:81]
	s_cbranch_execz .LBB0_377
	s_add_i32 s71, s37, 0xffffff00
	s_cmpk_lt_u32 s71, 0x1000
	s_cselect_b64 s[18:19], -1, 0
	s_cmp_lg_u32 s24, 0
	s_cselect_b64 s[28:29], -1, 0
	s_and_b64 s[18:19], s[18:19], s[28:29]
	s_andn2_b64 vcc, exec, s[78:79]
	s_mov_b64 s[78:79], -1
	s_cbranch_vccnz .LBB0_347
	s_xor_b64 s[78:79], s[74:75], -1
	s_and_saveexec_b64 s[28:29], s[78:79]
	s_xor_b64 s[80:81], exec, s[28:29]
	s_cbranch_execz .LBB0_278
	s_add_i32 s24, s70, 0xffffff00
	s_lshr_b32 s24, s24, 5
	s_load_dwordx2 s[28:29], s[48:49], 0x10
	s_lshl_b64 s[82:83], s[24:25], 10
	s_lshl_b32 s24, s70, 5
	s_and_b32 s24, s24, 0x3e0
	s_or_b32 s24, s82, s24
	v_mov_b32_e32 v33, s83
	v_or_b32_e32 v32, s24, v192
	v_lshlrev_b64 v[32:33], 8, v[32:33]
	s_waitcnt lgkmcnt(0)
	v_lshl_add_u64 v[32:33], s[28:29], 0, v[32:33]
	v_lshlrev_b32_e32 v176, 2, v194
	v_lshl_add_u64 v[32:33], v[32:33], 0, v[176:177]
	global_load_dwordx4 v[88:91], v[32:33], off
	global_load_dwordx4 v[92:95], v[32:33], off offset:256
	s_andn2_saveexec_b64 s[80:81], s[80:81]
	s_cbranch_execz .LBB0_280
	s_branch .LBB0_279

.LBB0_308:
	s_and_b32 s24, s27, 1
	s_mul_i32 s28, s24, 0xb000
	s_add_i32 s28, s28, 0
	v_add_u32_e32 v244, s28, v196
	v_lshl_add_u32 v246, v192, 2, s28
	v_lshl_add_u32 v176, s24, 12, v236
	s_waitcnt vmcnt(0)
	s_setprio 0
	v_add_u32_e32 v247, 0xa000, v246
	ds_read2_b64 v[96:99], v247 offset1:16
	ds_read_b128 v[100:103], v244 offset:33024
	ds_read_b128 v[104:107], v244 offset:32768
	ds_read_b128 v[116:119], v244 offset:24832
	ds_read_b128 v[136:139], v244 offset:24576
	ds_read_b128 v[140:143], v244 offset:16640
	ds_read_b128 v[144:147], v244 offset:16384
	ds_read_b128 v[148:151], v244 offset:8448
	ds_read_b128 v[168:171], v244 offset:8192
	ds_read_b128 v[172:175], v244 offset:256
	ds_read_b128 v[210:213], v244
	ds_read2_b64 v[120:123], v247 offset0:32 offset1:48
	ds_read_b128 v[160:163], v244 offset:512
	ds_read_b128 v[124:127], v244 offset:768
	ds_read_b128 v[214:217], v244 offset:8704
	ds_read_b128 v[132:135], v244 offset:8960
	ds_read_b128 v[152:155], v244 offset:16896
	ds_read_b128 v[108:111], v244 offset:17152
	ds_read_b128 v[164:167], v244 offset:25088
	ds_read_b128 v[128:131], v244 offset:25344
	ds_read_b128 v[156:159], v244 offset:33280
	ds_read_b128 v[112:115], v244 offset:33536
	v_lshl_add_u32 v245, v237, 2, v176
	s_waitcnt lgkmcnt(13)
	v_pk_mul_f32 v[248:249], v[90:91], v[170:171]
	v_pk_mul_f32 v[170:171], v[94:95], v[170:171]
	v_pk_fma_f32 v[248:249], v[88:89], v[168:169], v[248:249]
	v_pk_fma_f32 v[168:169], v[92:93], v[168:169], v[170:171]
	v_add_f32_e32 v170, v248, v249
	v_add_f32_e32 v168, v168, v169
	s_waitcnt lgkmcnt(11)
	v_pk_mul_f32 v[92:93], v[92:93], v[210:211]
	v_add_f32_dpp v169, v170, v170 quad_perm:[1,0,3,2] row_mask:0xf bank_mask:0xf bound_ctrl:1
	v_add_f32_dpp v168, v168, v168 quad_perm:[1,0,3,2] row_mask:0xf bank_mask:0xf bound_ctrl:1
	v_pk_mul_f32 v[88:89], v[88:89], v[210:211]
	v_add_f32_dpp v169, v169, v169 quad_perm:[2,3,0,1] row_mask:0xf bank_mask:0xf bound_ctrl:1
	v_add_f32_dpp v168, v168, v168 quad_perm:[2,3,0,1] row_mask:0xf bank_mask:0xf bound_ctrl:1
	v_pk_mul_f32 v[90:91], v[90:91], v[212:213]
	v_add_f32_dpp v170, v169, v169 row_ror:4 row_mask:0xf bank_mask:0xf bound_ctrl:1
	v_add_f32_dpp v168, v168, v168 row_ror:4 row_mask:0xf bank_mask:0xf bound_ctrl:1
	v_pk_fma_f32 v[92:93], v[96:97], v[136:137], v[92:93] op_sel:[1,0,0]
	v_pk_mul_f32 v[94:95], v[94:95], v[212:213]
	v_pk_fma_f32 v[88:89], v[96:97], v[136:137], v[88:89] op_sel_hi:[0,1,1]
	v_add_f32_dpp v136, v170, v170 row_ror:8 row_mask:0xf bank_mask:0xf bound_ctrl:1
	v_pk_fma_f32 v[90:91], v[96:97], v[138:139], v[90:91] op_sel_hi:[0,1,1]
	v_add_f32_dpp v168, v168, v168 row_ror:8 row_mask:0xf bank_mask:0xf bound_ctrl:1
	v_pk_fma_f32 v[94:95], v[96:97], v[138:139], v[94:95] op_sel:[1,0,0]
	v_pk_fma_f32 v[90:91], v[146:147], v[136:137], v[90:91] op_sel_hi:[1,0,1] neg_lo:[1,0,0] neg_hi:[1,0,0]
	v_pk_fma_f32 v[94:95], v[146:147], v[168:169], v[94:95] op_sel_hi:[1,0,1] neg_lo:[1,0,0] neg_hi:[1,0,0]
	v_pk_fma_f32 v[88:89], v[144:145], v[136:137], v[88:89] op_sel_hi:[1,0,1] neg_lo:[1,0,0] neg_hi:[1,0,0]
	v_pk_mul_f32 v[96:97], v[106:107], v[90:91]
	v_pk_fma_f32 v[92:93], v[144:145], v[168:169], v[92:93] op_sel_hi:[1,0,1] neg_lo:[1,0,0] neg_hi:[1,0,0]
	v_pk_mul_f32 v[168:169], v[106:107], v[94:95]
	v_pk_fma_f32 v[96:97], v[104:105], v[88:89], v[96:97]
	v_pk_fma_f32 v[168:169], v[104:105], v[92:93], v[168:169]
	v_add_f32_e32 v251, v96, v97
	v_pk_mul_f32 v[96:97], v[150:151], v[90:91]
	v_pk_mul_f32 v[104:105], v[150:151], v[94:95]
	v_pk_fma_f32 v[96:97], v[148:149], v[88:89], v[96:97]
	v_pk_fma_f32 v[104:105], v[148:149], v[92:93], v[104:105]
	v_add_f32_e32 v96, v96, v97
	v_add_f32_e32 v97, v104, v105
	v_pk_mul_f32 v[88:89], v[172:173], v[88:89]
	v_add_f32_dpp v96, v96, v96 quad_perm:[1,0,3,2] row_mask:0xf bank_mask:0xf bound_ctrl:1
	v_add_f32_dpp v97, v97, v97 quad_perm:[1,0,3,2] row_mask:0xf bank_mask:0xf bound_ctrl:1
	v_pk_mul_f32 v[90:91], v[174:175], v[90:91]
	v_add_f32_dpp v96, v96, v96 quad_perm:[2,3,0,1] row_mask:0xf bank_mask:0xf bound_ctrl:1
	v_add_f32_dpp v97, v97, v97 quad_perm:[2,3,0,1] row_mask:0xf bank_mask:0xf bound_ctrl:1
	v_pk_mul_f32 v[92:93], v[172:173], v[92:93]
	v_pk_mul_f32 v[94:95], v[174:175], v[94:95]
	v_add_f32_dpp v96, v96, v96 row_ror:4 row_mask:0xf bank_mask:0xf bound_ctrl:1
	v_add_f32_dpp v97, v97, v97 row_ror:4 row_mask:0xf bank_mask:0xf bound_ctrl:1
	v_pk_fma_f32 v[88:89], v[98:99], v[116:117], v[88:89] op_sel_hi:[0,1,1]
	v_pk_fma_f32 v[90:91], v[98:99], v[118:119], v[90:91] op_sel_hi:[0,1,1]
	v_pk_fma_f32 v[92:93], v[98:99], v[116:117], v[92:93] op_sel:[1,0,0]
	v_pk_fma_f32 v[94:95], v[98:99], v[118:119], v[94:95] op_sel:[1,0,0]
	v_add_f32_dpp v96, v96, v96 row_ror:8 row_mask:0xf bank_mask:0xf bound_ctrl:1
	v_add_f32_dpp v98, v97, v97 row_ror:8 row_mask:0xf bank_mask:0xf bound_ctrl:1
	v_pk_fma_f32 v[174:175], v[142:143], v[96:97], v[90:91] op_sel_hi:[1,0,1] neg_lo:[1,0,0] neg_hi:[1,0,0]
	v_pk_fma_f32 v[172:173], v[142:143], v[98:99], v[94:95] op_sel_hi:[1,0,1] neg_lo:[1,0,0] neg_hi:[1,0,0]
	v_pk_fma_f32 v[212:213], v[140:141], v[96:97], v[88:89] op_sel_hi:[1,0,1] neg_lo:[1,0,0] neg_hi:[1,0,0]
	v_pk_fma_f32 v[210:211], v[140:141], v[98:99], v[92:93] op_sel_hi:[1,0,1] neg_lo:[1,0,0] neg_hi:[1,0,0]
	v_pk_mul_f32 v[88:89], v[102:103], v[174:175]
	v_pk_mul_f32 v[90:91], v[102:103], v[172:173]
	v_pk_fma_f32 v[88:89], v[100:101], v[212:213], v[88:89]
	v_pk_fma_f32 v[90:91], v[100:101], v[210:211], v[90:91]
	v_add_f32_e32 v250, v168, v169
	v_add_f32_e32 v252, v88, v89
	v_add_f32_e32 v253, v90, v91
	ds_read2_b64 v[96:99], v247 offset0:64 offset1:80
	ds_read_b128 v[144:147], v244 offset:1024
	ds_read_b128 v[100:103], v244 offset:1280
	ds_read_b128 v[168:171], v244 offset:9216
	ds_read_b128 v[116:119], v244 offset:9472
	ds_read_b128 v[136:139], v244 offset:17408
	ds_read_b128 v[88:91], v244 offset:17664
	ds_read_b128 v[148:151], v244 offset:25600
	ds_read_b128 v[104:107], v244 offset:25856
	ds_read_b128 v[140:143], v244 offset:33792
	ds_read_b128 v[92:95], v244 offset:34048
	s_waitcnt lgkmcnt(14)
	v_pk_mul_f32 v[248:249], v[216:217], v[174:175]
	v_pk_mul_f32 v[216:217], v[216:217], v[172:173]
	v_pk_fma_f32 v[248:249], v[214:215], v[212:213], v[248:249]
	v_pk_fma_f32 v[214:215], v[214:215], v[210:211], v[216:217]
	v_add_f32_e32 v216, v248, v249
	v_cndmask_b32_e64 v248, v251, v250, s[6:7]
	v_cndmask_b32_e64 v249, v252, v253, s[6:7]
	v_cndmask_b32_e64 v250, v250, v251, s[6:7]
	v_cndmask_b32_e64 v251, v253, v252, s[6:7]
	v_add_f32_e32 v214, v214, v215
	v_add_f32_dpp v248, v248, v250 quad_perm:[1,0,3,2] row_mask:0xf bank_mask:0xf bound_ctrl:1
	v_add_f32_dpp v249, v249, v251 quad_perm:[1,0,3,2] row_mask:0xf bank_mask:0xf bound_ctrl:1
	v_add_f32_dpp v215, v216, v216 quad_perm:[1,0,3,2] row_mask:0xf bank_mask:0xf bound_ctrl:1
	v_add_f32_dpp v214, v214, v214 quad_perm:[1,0,3,2] row_mask:0xf bank_mask:0xf bound_ctrl:1
	v_cndmask_b32_e64 v250, v248, v249, s[8:9]
	v_cndmask_b32_e64 v248, v249, v248, s[8:9]
	v_add_f32_dpp v215, v215, v215 quad_perm:[2,3,0,1] row_mask:0xf bank_mask:0xf bound_ctrl:1
	v_add_f32_dpp v216, v214, v214 quad_perm:[2,3,0,1] row_mask:0xf bank_mask:0xf bound_ctrl:1
	v_add_f32_dpp v248, v250, v248 quad_perm:[2,3,0,1] row_mask:0xf bank_mask:0xf bound_ctrl:1
	v_add_f32_dpp v214, v215, v215 row_ror:4 row_mask:0xf bank_mask:0xf bound_ctrl:1
	v_add_f32_dpp v215, v216, v216 row_ror:4 row_mask:0xf bank_mask:0xf bound_ctrl:1
	v_mov_b32_e32 v216, v177
	v_mov_b32_e32 v217, v177
	v_add_f32_dpp v248, v248, v248 row_ror:4 row_mask:0xf bank_mask:0xf bound_ctrl:1
	v_mov_b32_e32 v249, v177
	v_mov_b32_dpp v216, v214 row_ror:8 row_mask:0xf bank_mask:0xf
	v_mov_b32_dpp v217, v215 row_ror:8 row_mask:0xf bank_mask:0xf
	v_mov_b32_dpp v249, v248 row_ror:8 row_mask:0xf bank_mask:0xf
	v_add_u32_e32 v245, v245, v240
	s_and_saveexec_b64 s[78:79], s[10:11]
	v_add_f32_e32 v248, v248, v249
	ds_write_b32 v245, v248
	s_or_b64 exec, exec, s[78:79]
	v_pk_mul_f32 v[212:213], v[160:161], v[212:213]
	v_pk_mul_f32 v[174:175], v[162:163], v[174:175]
	v_pk_mul_f32 v[160:161], v[160:161], v[210:211]
	v_pk_mul_f32 v[162:163], v[162:163], v[172:173]
	v_pk_fma_f32 v[212:213], v[164:165], v[120:121], v[212:213] op_sel_hi:[1,0,1]
	v_pk_fma_f32 v[174:175], v[166:167], v[120:121], v[174:175] op_sel_hi:[1,0,1]
	v_pk_fma_f32 v[160:161], v[164:165], v[120:121], v[160:161] op_sel:[0,1,0]
	v_pk_fma_f32 v[120:121], v[166:167], v[120:121], v[162:163] op_sel:[0,1,0]
	v_add_f32_e32 v162, v214, v216
	v_add_f32_e32 v164, v215, v217
	v_pk_fma_f32 v[166:167], v[152:153], v[162:163], v[212:213] op_sel_hi:[1,0,1] neg_lo:[1,0,0] neg_hi:[1,0,0]
	v_pk_fma_f32 v[162:163], v[154:155], v[162:163], v[174:175] op_sel_hi:[1,0,1] neg_lo:[1,0,0] neg_hi:[1,0,0]
	v_pk_fma_f32 v[120:121], v[154:155], v[164:165], v[120:121] op_sel_hi:[1,0,1] neg_lo:[1,0,0] neg_hi:[1,0,0]
	s_waitcnt lgkmcnt(12)
	v_pk_mul_f32 v[154:155], v[158:159], v[162:163]
	v_pk_fma_f32 v[152:153], v[152:153], v[164:165], v[160:161] op_sel_hi:[1,0,1] neg_lo:[1,0,0] neg_hi:[1,0,0]
	v_pk_fma_f32 v[154:155], v[156:157], v[166:167], v[154:155]
	v_pk_mul_f32 v[158:159], v[158:159], v[120:121]
	v_add_f32_e32 v250, v154, v155
	v_pk_mul_f32 v[154:155], v[134:135], v[162:163]
	v_pk_mul_f32 v[134:135], v[134:135], v[120:121]
	v_pk_fma_f32 v[154:155], v[132:133], v[166:167], v[154:155]
	v_pk_fma_f32 v[132:133], v[132:133], v[152:153], v[134:135]
	v_add_f32_e32 v154, v154, v155
	v_add_f32_e32 v155, v132, v133
	v_pk_mul_f32 v[132:133], v[124:125], v[166:167]
	v_pk_mul_f32 v[134:135], v[126:127], v[162:163]
	v_pk_mul_f32 v[124:125], v[124:125], v[152:153]
	v_pk_mul_f32 v[120:121], v[126:127], v[120:121]
	v_pk_fma_f32 v[132:133], v[128:129], v[122:123], v[132:133] op_sel_hi:[1,0,1]
	v_pk_fma_f32 v[134:135], v[130:131], v[122:123], v[134:135] op_sel_hi:[1,0,1]
	v_pk_fma_f32 v[124:125], v[128:129], v[122:123], v[124:125] op_sel:[0,1,0]
	v_pk_fma_f32 v[120:121], v[130:131], v[122:123], v[120:121] op_sel:[0,1,0]
	v_add_f32_dpp v122, v154, v154 quad_perm:[1,0,3,2] row_mask:0xf bank_mask:0xf bound_ctrl:1
	v_add_f32_dpp v123, v155, v155 quad_perm:[1,0,3,2] row_mask:0xf bank_mask:0xf bound_ctrl:1
	v_pk_fma_f32 v[156:157], v[156:157], v[152:153], v[158:159]
	v_add_f32_dpp v122, v122, v122 quad_perm:[2,3,0,1] row_mask:0xf bank_mask:0xf bound_ctrl:1
	v_add_f32_dpp v123, v123, v123 quad_perm:[2,3,0,1] row_mask:0xf bank_mask:0xf bound_ctrl:1
	v_add_f32_e32 v251, v156, v157
	v_add_f32_dpp v122, v122, v122 row_ror:4 row_mask:0xf bank_mask:0xf bound_ctrl:1
	v_add_f32_dpp v123, v123, v123 row_ror:4 row_mask:0xf bank_mask:0xf bound_ctrl:1
	s_nop 0
	v_add_f32_dpp v122, v122, v122 row_ror:8 row_mask:0xf bank_mask:0xf bound_ctrl:1
	v_add_f32_dpp v126, v123, v123 row_ror:8 row_mask:0xf bank_mask:0xf bound_ctrl:1
	v_pk_fma_f32 v[212:213], v[110:111], v[122:123], v[134:135] op_sel_hi:[1,0,1] neg_lo:[1,0,0] neg_hi:[1,0,0]
	v_pk_fma_f32 v[210:211], v[110:111], v[126:127], v[120:121] op_sel_hi:[1,0,1] neg_lo:[1,0,0] neg_hi:[1,0,0]
	v_pk_fma_f32 v[216:217], v[108:109], v[122:123], v[132:133] op_sel_hi:[1,0,1] neg_lo:[1,0,0] neg_hi:[1,0,0]
	v_pk_fma_f32 v[214:215], v[108:109], v[126:127], v[124:125] op_sel_hi:[1,0,1] neg_lo:[1,0,0] neg_hi:[1,0,0]
	s_waitcnt lgkmcnt(11)
	v_pk_mul_f32 v[108:109], v[114:115], v[212:213]
	v_pk_mul_f32 v[110:111], v[114:115], v[210:211]
	v_pk_fma_f32 v[108:109], v[112:113], v[216:217], v[108:109]
	v_pk_fma_f32 v[110:111], v[112:113], v[214:215], v[110:111]
	v_add_f32_e32 v252, v108, v109
	v_add_f32_e32 v253, v110, v111
	ds_read2_b64 v[120:123], v247 offset0:96 offset1:112
	ds_read_b128 v[160:163], v244 offset:1536
	ds_read_b128 v[124:127], v244 offset:1792
	ds_read_b128 v[172:175], v244 offset:9728
	ds_read_b128 v[132:135], v244 offset:9984
	ds_read_b128 v[152:155], v244 offset:17920
	ds_read_b128 v[108:111], v244 offset:18176
	ds_read_b128 v[164:167], v244 offset:26112
	ds_read_b128 v[128:131], v244 offset:26368
	ds_read_b128 v[156:159], v244 offset:34304
	ds_read_b128 v[112:115], v244 offset:34560
	s_waitcnt lgkmcnt(14)
	v_pk_mul_f32 v[248:249], v[170:171], v[212:213]
	v_pk_mul_f32 v[170:171], v[170:171], v[210:211]
	v_pk_fma_f32 v[248:249], v[168:169], v[216:217], v[248:249]
	v_pk_fma_f32 v[168:169], v[168:169], v[214:215], v[170:171]
	v_add_f32_e32 v170, v248, v249
	v_cndmask_b32_e64 v248, v250, v251, s[6:7]
	v_cndmask_b32_e64 v249, v252, v253, s[6:7]
	v_cndmask_b32_e64 v250, v251, v250, s[6:7]
	v_cndmask_b32_e64 v251, v253, v252, s[6:7]
	v_add_f32_e32 v168, v168, v169
	v_add_f32_dpp v248, v248, v250 quad_perm:[1,0,3,2] row_mask:0xf bank_mask:0xf bound_ctrl:1
	v_add_f32_dpp v249, v249, v251 quad_perm:[1,0,3,2] row_mask:0xf bank_mask:0xf bound_ctrl:1
	v_add_f32_dpp v169, v170, v170 quad_perm:[1,0,3,2] row_mask:0xf bank_mask:0xf bound_ctrl:1
	v_add_f32_dpp v168, v168, v168 quad_perm:[1,0,3,2] row_mask:0xf bank_mask:0xf bound_ctrl:1
	v_cndmask_b32_e64 v250, v248, v249, s[8:9]
	v_cndmask_b32_e64 v248, v249, v248, s[8:9]
	v_add_f32_dpp v169, v169, v169 quad_perm:[2,3,0,1] row_mask:0xf bank_mask:0xf bound_ctrl:1
	v_add_f32_dpp v170, v168, v168 quad_perm:[2,3,0,1] row_mask:0xf bank_mask:0xf bound_ctrl:1
	v_add_f32_dpp v248, v250, v248 quad_perm:[2,3,0,1] row_mask:0xf bank_mask:0xf bound_ctrl:1
	v_add_f32_dpp v168, v169, v169 row_ror:4 row_mask:0xf bank_mask:0xf bound_ctrl:1
	v_add_f32_dpp v169, v170, v170 row_ror:4 row_mask:0xf bank_mask:0xf bound_ctrl:1
	v_mov_b32_e32 v170, 0
	v_mov_b32_e32 v171, 0
	v_add_f32_dpp v248, v248, v248 row_ror:4 row_mask:0xf bank_mask:0xf bound_ctrl:1
	v_mov_b32_e32 v249, 0
	v_mov_b32_dpp v170, v168 row_ror:8 row_mask:0xf bank_mask:0xf
	v_mov_b32_dpp v171, v169 row_ror:8 row_mask:0xf bank_mask:0xf
	v_mov_b32_dpp v249, v248 row_ror:8 row_mask:0xf bank_mask:0xf
	s_and_saveexec_b64 s[78:79], s[10:11]
	v_add_f32_e32 v248, v248, v249
	ds_write_b32 v245, v248 offset:256
	s_or_b64 exec, exec, s[78:79]
	v_pk_mul_f32 v[216:217], v[144:145], v[216:217]
	v_pk_mul_f32 v[212:213], v[146:147], v[212:213]
	v_pk_mul_f32 v[144:145], v[144:145], v[214:215]
	v_pk_mul_f32 v[146:147], v[146:147], v[210:211]
	v_pk_fma_f32 v[216:217], v[148:149], v[96:97], v[216:217] op_sel_hi:[1,0,1]
	v_pk_fma_f32 v[212:213], v[150:151], v[96:97], v[212:213] op_sel_hi:[1,0,1]
	v_pk_fma_f32 v[144:145], v[148:149], v[96:97], v[144:145] op_sel:[0,1,0]
	v_pk_fma_f32 v[96:97], v[150:151], v[96:97], v[146:147] op_sel:[0,1,0]
	v_add_f32_e32 v146, v168, v170
	v_add_f32_e32 v148, v169, v171
	v_pk_fma_f32 v[150:151], v[136:137], v[146:147], v[216:217] op_sel_hi:[1,0,1] neg_lo:[1,0,0] neg_hi:[1,0,0]
	v_pk_fma_f32 v[146:147], v[138:139], v[146:147], v[212:213] op_sel_hi:[1,0,1] neg_lo:[1,0,0] neg_hi:[1,0,0]
	v_pk_fma_f32 v[96:97], v[138:139], v[148:149], v[96:97] op_sel_hi:[1,0,1] neg_lo:[1,0,0] neg_hi:[1,0,0]
	s_waitcnt lgkmcnt(12)
	v_pk_mul_f32 v[138:139], v[142:143], v[146:147]
	v_pk_fma_f32 v[136:137], v[136:137], v[148:149], v[144:145] op_sel_hi:[1,0,1] neg_lo:[1,0,0] neg_hi:[1,0,0]
	v_pk_fma_f32 v[138:139], v[140:141], v[150:151], v[138:139]
	v_pk_mul_f32 v[142:143], v[142:143], v[96:97]
	s_nop 0
	v_pk_fma_f32 v[140:141], v[140:141], v[136:137], v[142:143]
	v_add_f32_e32 v142, v138, v139
	v_pk_mul_f32 v[138:139], v[118:119], v[146:147]
	v_pk_mul_f32 v[118:119], v[118:119], v[96:97]
	v_pk_fma_f32 v[138:139], v[116:117], v[150:151], v[138:139]
	v_pk_fma_f32 v[116:117], v[116:117], v[136:137], v[118:119]
	v_add_f32_e32 v138, v138, v139
	v_add_f32_e32 v139, v116, v117
	v_pk_mul_f32 v[96:97], v[102:103], v[96:97]
	v_pk_mul_f32 v[118:119], v[102:103], v[146:147]
	v_pk_fma_f32 v[102:103], v[106:107], v[98:99], v[96:97] op_sel:[0,1,0]
	v_add_f32_dpp v96, v138, v138 quad_perm:[1,0,3,2] row_mask:0xf bank_mask:0xf bound_ctrl:1
	v_add_f32_dpp v97, v139, v139 quad_perm:[1,0,3,2] row_mask:0xf bank_mask:0xf bound_ctrl:1
	v_pk_mul_f32 v[116:117], v[100:101], v[150:151]
	v_add_f32_dpp v96, v96, v96 quad_perm:[2,3,0,1] row_mask:0xf bank_mask:0xf bound_ctrl:1
	v_add_f32_dpp v97, v97, v97 quad_perm:[2,3,0,1] row_mask:0xf bank_mask:0xf bound_ctrl:1
	v_pk_mul_f32 v[100:101], v[100:101], v[136:137]
	v_add_f32_dpp v96, v96, v96 row_ror:4 row_mask:0xf bank_mask:0xf bound_ctrl:1
	v_add_f32_dpp v97, v97, v97 row_ror:4 row_mask:0xf bank_mask:0xf bound_ctrl:1
	v_pk_fma_f32 v[116:117], v[104:105], v[98:99], v[116:117] op_sel_hi:[1,0,1]
	v_pk_fma_f32 v[118:119], v[106:107], v[98:99], v[118:119] op_sel_hi:[1,0,1]
	v_pk_fma_f32 v[104:105], v[104:105], v[98:99], v[100:101] op_sel:[0,1,0]
	v_add_f32_dpp v96, v96, v96 row_ror:8 row_mask:0xf bank_mask:0xf bound_ctrl:1
	v_add_f32_dpp v106, v97, v97 row_ror:8 row_mask:0xf bank_mask:0xf bound_ctrl:1
	v_pk_fma_f32 v[100:101], v[88:89], v[96:97], v[116:117] op_sel_hi:[1,0,1] neg_lo:[1,0,0] neg_hi:[1,0,0]
	v_pk_fma_f32 v[96:97], v[90:91], v[96:97], v[118:119] op_sel_hi:[1,0,1] neg_lo:[1,0,0] neg_hi:[1,0,0]
	v_pk_fma_f32 v[98:99], v[88:89], v[106:107], v[104:105] op_sel_hi:[1,0,1] neg_lo:[1,0,0] neg_hi:[1,0,0]
	v_pk_fma_f32 v[88:89], v[90:91], v[106:107], v[102:103] op_sel_hi:[1,0,1] neg_lo:[1,0,0] neg_hi:[1,0,0]
	s_waitcnt lgkmcnt(11)
	v_pk_mul_f32 v[90:91], v[94:95], v[96:97]
	v_pk_mul_f32 v[94:95], v[94:95], v[88:89]
	v_pk_fma_f32 v[90:91], v[92:93], v[100:101], v[90:91]
	v_pk_fma_f32 v[92:93], v[92:93], v[98:99], v[94:95]
	v_add_f32_e32 v94, v90, v91
	v_add_f32_e32 v95, v92, v93
	v_add_f32_e32 v140, v140, v141
	s_waitcnt lgkmcnt(7)
	v_pk_mul_f32 v[90:91], v[174:175], v[96:97]
	v_pk_mul_f32 v[92:93], v[174:175], v[88:89]
	v_pk_fma_f32 v[90:91], v[172:173], v[100:101], v[90:91]
	v_pk_fma_f32 v[92:93], v[172:173], v[98:99], v[92:93]
	v_cndmask_b32_e64 v102, v142, v140, s[6:7]
	v_cndmask_b32_e64 v103, v94, v95, s[6:7]
	v_cndmask_b32_e64 v104, v140, v142, s[6:7]
	v_cndmask_b32_e64 v94, v95, v94, s[6:7]
	v_add_f32_e32 v90, v90, v91
	v_add_f32_e32 v91, v92, v93
	v_add_f32_dpp v95, v102, v104 quad_perm:[1,0,3,2] row_mask:0xf bank_mask:0xf bound_ctrl:1
	v_add_f32_dpp v94, v103, v94 quad_perm:[1,0,3,2] row_mask:0xf bank_mask:0xf bound_ctrl:1
	v_add_f32_dpp v90, v90, v90 quad_perm:[1,0,3,2] row_mask:0xf bank_mask:0xf bound_ctrl:1
	v_add_f32_dpp v91, v91, v91 quad_perm:[1,0,3,2] row_mask:0xf bank_mask:0xf bound_ctrl:1
	v_cndmask_b32_e64 v102, v95, v94, s[8:9]
	v_cndmask_b32_e64 v94, v94, v95, s[8:9]
	v_add_f32_dpp v90, v90, v90 quad_perm:[2,3,0,1] row_mask:0xf bank_mask:0xf bound_ctrl:1
	v_add_f32_dpp v91, v91, v91 quad_perm:[2,3,0,1] row_mask:0xf bank_mask:0xf bound_ctrl:1
	v_add_f32_dpp v94, v102, v94 quad_perm:[2,3,0,1] row_mask:0xf bank_mask:0xf bound_ctrl:1
	v_add_f32_dpp v90, v90, v90 row_ror:4 row_mask:0xf bank_mask:0xf bound_ctrl:1
	v_add_f32_dpp v91, v91, v91 row_ror:4 row_mask:0xf bank_mask:0xf bound_ctrl:1
	v_mov_b32_e32 v92, 0
	v_mov_b32_e32 v93, 0
	v_add_f32_dpp v94, v94, v94 row_ror:4 row_mask:0xf bank_mask:0xf bound_ctrl:1
	v_mov_b32_e32 v95, 0
	v_mov_b32_dpp v92, v90 row_ror:8 row_mask:0xf bank_mask:0xf
	v_mov_b32_dpp v93, v91 row_ror:8 row_mask:0xf bank_mask:0xf
	v_mov_b32_dpp v95, v94 row_ror:8 row_mask:0xf bank_mask:0xf
	s_and_saveexec_b64 s[78:79], s[10:11]
	v_add_f32_e32 v94, v94, v95
	ds_write_b32 v245, v94 offset:512
	s_or_b64 exec, exec, s[78:79]
	v_pk_mul_f32 v[94:95], v[160:161], v[100:101]
	v_pk_mul_f32 v[96:97], v[162:163], v[96:97]
	v_pk_mul_f32 v[88:89], v[162:163], v[88:89]
	s_waitcnt lgkmcnt(3)
	v_pk_fma_f32 v[94:95], v[164:165], v[120:121], v[94:95] op_sel_hi:[1,0,1]
	v_pk_fma_f32 v[96:97], v[166:167], v[120:121], v[96:97] op_sel_hi:[1,0,1]
	v_pk_mul_f32 v[98:99], v[160:161], v[98:99]
	v_pk_fma_f32 v[88:89], v[166:167], v[120:121], v[88:89] op_sel:[0,1,0]
	v_add_f32_e32 v90, v90, v92
	v_add_f32_e32 v92, v91, v93
	v_pk_fma_f32 v[98:99], v[164:165], v[120:121], v[98:99] op_sel:[0,1,0]
	v_pk_fma_f32 v[94:95], v[152:153], v[90:91], v[94:95] op_sel_hi:[1,0,1] neg_lo:[1,0,0] neg_hi:[1,0,0]
	v_pk_fma_f32 v[90:91], v[154:155], v[90:91], v[96:97] op_sel_hi:[1,0,1] neg_lo:[1,0,0] neg_hi:[1,0,0]
	v_pk_fma_f32 v[88:89], v[154:155], v[92:93], v[88:89] op_sel_hi:[1,0,1] neg_lo:[1,0,0] neg_hi:[1,0,0]
	v_pk_fma_f32 v[96:97], v[152:153], v[92:93], v[98:99] op_sel_hi:[1,0,1] neg_lo:[1,0,0] neg_hi:[1,0,0]
	s_waitcnt lgkmcnt(1)
	v_pk_mul_f32 v[92:93], v[158:159], v[90:91]
	v_pk_mul_f32 v[98:99], v[158:159], v[88:89]
	v_pk_fma_f32 v[92:93], v[156:157], v[94:95], v[92:93]
	v_pk_fma_f32 v[98:99], v[156:157], v[96:97], v[98:99]
	v_add_f32_e32 v101, v92, v93
	v_add_f32_e32 v102, v98, v99
	v_pk_mul_f32 v[92:93], v[134:135], v[90:91]
	v_pk_mul_f32 v[98:99], v[134:135], v[88:89]
	v_pk_fma_f32 v[92:93], v[132:133], v[94:95], v[92:93]
	v_pk_fma_f32 v[98:99], v[132:133], v[96:97], v[98:99]
	v_add_f32_e32 v100, v92, v93
	v_add_f32_e32 v98, v98, v99
	v_pk_mul_f32 v[88:89], v[126:127], v[88:89]
	v_pk_mul_f32 v[92:93], v[124:125], v[94:95]
	v_pk_mul_f32 v[94:95], v[124:125], v[96:97]
	v_pk_fma_f32 v[96:97], v[130:131], v[122:123], v[88:89] op_sel:[0,1,0]
	v_add_f32_dpp v88, v100, v100 quad_perm:[1,0,3,2] row_mask:0xf bank_mask:0xf bound_ctrl:1
	v_add_f32_dpp v89, v98, v98 quad_perm:[1,0,3,2] row_mask:0xf bank_mask:0xf bound_ctrl:1
	v_pk_mul_f32 v[90:91], v[126:127], v[90:91]
	v_add_f32_dpp v88, v88, v88 quad_perm:[2,3,0,1] row_mask:0xf bank_mask:0xf bound_ctrl:1
	v_add_f32_dpp v89, v89, v89 quad_perm:[2,3,0,1] row_mask:0xf bank_mask:0xf bound_ctrl:1
	v_pk_fma_f32 v[92:93], v[128:129], v[122:123], v[92:93] op_sel_hi:[1,0,1]
	v_add_f32_dpp v88, v88, v88 row_ror:4 row_mask:0xf bank_mask:0xf bound_ctrl:1
	v_add_f32_dpp v89, v89, v89 row_ror:4 row_mask:0xf bank_mask:0xf bound_ctrl:1
	v_pk_fma_f32 v[90:91], v[130:131], v[122:123], v[90:91] op_sel_hi:[1,0,1]
	v_pk_fma_f32 v[94:95], v[128:129], v[122:123], v[94:95] op_sel:[0,1,0]
	v_add_f32_dpp v98, v88, v88 row_ror:8 row_mask:0xf bank_mask:0xf bound_ctrl:1
	v_add_f32_dpp v100, v89, v89 row_ror:8 row_mask:0xf bank_mask:0xf bound_ctrl:1
	v_pk_fma_f32 v[88:89], v[108:109], v[98:99], v[92:93] op_sel_hi:[1,0,1] neg_lo:[1,0,0] neg_hi:[1,0,0]
	v_pk_fma_f32 v[90:91], v[110:111], v[98:99], v[90:91] op_sel_hi:[1,0,1] neg_lo:[1,0,0] neg_hi:[1,0,0]
	v_pk_fma_f32 v[92:93], v[108:109], v[100:101], v[94:95] op_sel_hi:[1,0,1] neg_lo:[1,0,0] neg_hi:[1,0,0]
	v_pk_fma_f32 v[94:95], v[110:111], v[100:101], v[96:97] op_sel_hi:[1,0,1] neg_lo:[1,0,0] neg_hi:[1,0,0]
	s_waitcnt lgkmcnt(0)
	v_pk_mul_f32 v[96:97], v[114:115], v[90:91]
	v_pk_mul_f32 v[98:99], v[114:115], v[94:95]
	v_pk_fma_f32 v[96:97], v[112:113], v[88:89], v[96:97]
	v_pk_fma_f32 v[98:99], v[112:113], v[92:93], v[98:99]
	v_add_f32_e32 v96, v96, v97
	v_add_f32_e32 v97, v98, v99
	v_cndmask_b32_e64 v98, v101, v102, s[6:7]
	v_cndmask_b32_e64 v99, v96, v97, s[6:7]
	v_cndmask_b32_e64 v100, v102, v101, s[6:7]
	v_cndmask_b32_e64 v96, v97, v96, s[6:7]
	s_nop 0
	v_add_f32_dpp v97, v98, v100 quad_perm:[1,0,3,2] row_mask:0xf bank_mask:0xf bound_ctrl:1
	v_add_f32_dpp v96, v99, v96 quad_perm:[1,0,3,2] row_mask:0xf bank_mask:0xf bound_ctrl:1
	v_cndmask_b32_e64 v98, v97, v96, s[8:9]
	v_cndmask_b32_e64 v96, v96, v97, s[8:9]
	v_mov_b32_e32 v97, 0
	s_nop 0
	v_add_f32_dpp v96, v98, v96 quad_perm:[2,3,0,1] row_mask:0xf bank_mask:0xf bound_ctrl:1
	s_nop 1
	v_add_f32_dpp v96, v96, v96 row_ror:4 row_mask:0xf bank_mask:0xf bound_ctrl:1
	s_nop 1
	v_mov_b32_dpp v97, v96 row_ror:8 row_mask:0xf bank_mask:0xf
	s_and_saveexec_b64 s[78:79], s[10:11]
	v_add3_u32 v98, v176, v239, v197
	v_add_f32_e32 v96, v96, v97
	ds_write_b32 v98, v96 offset:768
	s_or_b64 exec, exec, s[78:79]
	s_setprio 0
	s_add_i32 s24, s70, 0xffffff00
	s_lshr_b32 s24, s24, 5
	s_lshl_b64 s[28:29], s[24:25], 10
	s_lshl_b32 s24, s70, 5
	s_and_b32 s24, s24, 0x3e0
	s_or_b32 s24, s28, s24
	v_mov_b32_e32 v97, s29
	v_or_b32_e32 v96, s24, v192
	v_lshlrev_b64 v[96:97], 8, v[96:97]
	s_add_i32 s24, s70, s94
	v_lshl_add_u64 v[96:97], v[198:199], 0, v[96:97]
	s_cmpk_gt_i32 s24, 0x10ff
	global_store_dwordx4 v[96:97], v[88:91], off
	global_store_dwordx4 v[96:97], v[92:95], off offset:256
	s_cbranch_scc1 .LBB0_327
	s_setprio 0
	ds_read2_b64 v[88:91], v247 offset0:128 offset1:144
	ds_read_b128 v[92:95], v244 offset:35072
	ds_read_b128 v[96:99], v244 offset:34816
	ds_read_b128 v[108:111], v244 offset:26880
	ds_read_b128 v[128:131], v244 offset:26624
	ds_read_b128 v[132:135], v244 offset:18688
	ds_read_b128 v[136:139], v244 offset:18432
	ds_read_b128 v[140:143], v244 offset:10496
	ds_read_b128 v[160:163], v244 offset:10240
	ds_read_b128 v[164:167], v244 offset:2304
	ds_read_b128 v[168:171], v244 offset:2048
	ds_read2_b64 v[112:115], v247 offset0:160 offset1:176
	ds_read_b128 v[152:155], v244 offset:2560
	ds_read_b128 v[116:119], v244 offset:2816
	ds_read_b128 v[172:175], v244 offset:10752
	ds_read_b128 v[124:127], v244 offset:11008
	ds_read_b128 v[144:147], v244 offset:18944
	ds_read_b128 v[100:103], v244 offset:19200
	ds_read_b128 v[156:159], v244 offset:27136
	ds_read_b128 v[120:123], v244 offset:27392
	ds_read_b128 v[148:151], v244 offset:35328
	ds_read_b128 v[104:107], v244 offset:35584
	s_waitcnt lgkmcnt(13)
	v_pk_mul_f32 v[210:211], v[82:83], v[162:163]
	v_pk_mul_f32 v[162:163], v[86:87], v[162:163]
	v_pk_fma_f32 v[210:211], v[80:81], v[160:161], v[210:211]
	v_pk_fma_f32 v[160:161], v[84:85], v[160:161], v[162:163]
	v_add_f32_e32 v162, v210, v211
	v_add_f32_e32 v160, v160, v161
	s_waitcnt lgkmcnt(11)
	v_pk_mul_f32 v[84:85], v[84:85], v[168:169]
	v_add_f32_dpp v161, v162, v162 quad_perm:[1,0,3,2] row_mask:0xf bank_mask:0xf bound_ctrl:1
	v_add_f32_dpp v160, v160, v160 quad_perm:[1,0,3,2] row_mask:0xf bank_mask:0xf bound_ctrl:1
	v_pk_mul_f32 v[80:81], v[80:81], v[168:169]
	v_add_f32_dpp v161, v161, v161 quad_perm:[2,3,0,1] row_mask:0xf bank_mask:0xf bound_ctrl:1
	v_add_f32_dpp v160, v160, v160 quad_perm:[2,3,0,1] row_mask:0xf bank_mask:0xf bound_ctrl:1
	v_pk_mul_f32 v[82:83], v[82:83], v[170:171]
	v_add_f32_dpp v162, v161, v161 row_ror:4 row_mask:0xf bank_mask:0xf bound_ctrl:1
	v_add_f32_dpp v160, v160, v160 row_ror:4 row_mask:0xf bank_mask:0xf bound_ctrl:1
	v_pk_fma_f32 v[84:85], v[88:89], v[128:129], v[84:85] op_sel:[1,0,0]
	v_pk_mul_f32 v[86:87], v[86:87], v[170:171]
	v_pk_fma_f32 v[80:81], v[88:89], v[128:129], v[80:81] op_sel_hi:[0,1,1]
	v_add_f32_dpp v128, v162, v162 row_ror:8 row_mask:0xf bank_mask:0xf bound_ctrl:1
	v_pk_fma_f32 v[82:83], v[88:89], v[130:131], v[82:83] op_sel_hi:[0,1,1]
	v_add_f32_dpp v160, v160, v160 row_ror:8 row_mask:0xf bank_mask:0xf bound_ctrl:1
	v_pk_fma_f32 v[86:87], v[88:89], v[130:131], v[86:87] op_sel:[1,0,0]
	v_pk_fma_f32 v[82:83], v[138:139], v[128:129], v[82:83] op_sel_hi:[1,0,1] neg_lo:[1,0,0] neg_hi:[1,0,0]
	v_pk_fma_f32 v[86:87], v[138:139], v[160:161], v[86:87] op_sel_hi:[1,0,1] neg_lo:[1,0,0] neg_hi:[1,0,0]
	v_pk_fma_f32 v[80:81], v[136:137], v[128:129], v[80:81] op_sel_hi:[1,0,1] neg_lo:[1,0,0] neg_hi:[1,0,0]
	v_pk_mul_f32 v[88:89], v[98:99], v[82:83]
	v_pk_fma_f32 v[84:85], v[136:137], v[160:161], v[84:85] op_sel_hi:[1,0,1] neg_lo:[1,0,0] neg_hi:[1,0,0]
	v_pk_mul_f32 v[160:161], v[98:99], v[86:87]
	v_pk_fma_f32 v[88:89], v[96:97], v[80:81], v[88:89]
	v_pk_fma_f32 v[160:161], v[96:97], v[84:85], v[160:161]
	v_add_f32_e32 v213, v88, v89
	v_pk_mul_f32 v[88:89], v[142:143], v[82:83]
	v_pk_mul_f32 v[96:97], v[142:143], v[86:87]
	v_pk_fma_f32 v[88:89], v[140:141], v[80:81], v[88:89]
	v_pk_fma_f32 v[96:97], v[140:141], v[84:85], v[96:97]
	v_add_f32_e32 v88, v88, v89
	v_add_f32_e32 v89, v96, v97
	v_pk_mul_f32 v[80:81], v[164:165], v[80:81]
	v_add_f32_dpp v88, v88, v88 quad_perm:[1,0,3,2] row_mask:0xf bank_mask:0xf bound_ctrl:1
	v_add_f32_dpp v89, v89, v89 quad_perm:[1,0,3,2] row_mask:0xf bank_mask:0xf bound_ctrl:1
	v_pk_mul_f32 v[82:83], v[166:167], v[82:83]
	v_add_f32_dpp v88, v88, v88 quad_perm:[2,3,0,1] row_mask:0xf bank_mask:0xf bound_ctrl:1
	v_add_f32_dpp v89, v89, v89 quad_perm:[2,3,0,1] row_mask:0xf bank_mask:0xf bound_ctrl:1
	v_pk_mul_f32 v[84:85], v[164:165], v[84:85]
	v_pk_mul_f32 v[86:87], v[166:167], v[86:87]
	v_add_f32_dpp v88, v88, v88 row_ror:4 row_mask:0xf bank_mask:0xf bound_ctrl:1
	v_add_f32_dpp v89, v89, v89 row_ror:4 row_mask:0xf bank_mask:0xf bound_ctrl:1
	v_pk_fma_f32 v[80:81], v[90:91], v[108:109], v[80:81] op_sel_hi:[0,1,1]
	v_pk_fma_f32 v[82:83], v[90:91], v[110:111], v[82:83] op_sel_hi:[0,1,1]
	v_pk_fma_f32 v[84:85], v[90:91], v[108:109], v[84:85] op_sel:[1,0,0]
	v_pk_fma_f32 v[86:87], v[90:91], v[110:111], v[86:87] op_sel:[1,0,0]
	v_add_f32_dpp v88, v88, v88 row_ror:8 row_mask:0xf bank_mask:0xf bound_ctrl:1
	v_add_f32_dpp v90, v89, v89 row_ror:8 row_mask:0xf bank_mask:0xf bound_ctrl:1
	v_pk_fma_f32 v[166:167], v[134:135], v[88:89], v[82:83] op_sel_hi:[1,0,1] neg_lo:[1,0,0] neg_hi:[1,0,0]
	v_pk_fma_f32 v[164:165], v[134:135], v[90:91], v[86:87] op_sel_hi:[1,0,1] neg_lo:[1,0,0] neg_hi:[1,0,0]
	v_pk_fma_f32 v[170:171], v[132:133], v[88:89], v[80:81] op_sel_hi:[1,0,1] neg_lo:[1,0,0] neg_hi:[1,0,0]
	v_pk_fma_f32 v[168:169], v[132:133], v[90:91], v[84:85] op_sel_hi:[1,0,1] neg_lo:[1,0,0] neg_hi:[1,0,0]
	v_pk_mul_f32 v[80:81], v[94:95], v[166:167]
	v_pk_mul_f32 v[82:83], v[94:95], v[164:165]
	v_pk_fma_f32 v[80:81], v[92:93], v[170:171], v[80:81]
	v_pk_fma_f32 v[82:83], v[92:93], v[168:169], v[82:83]
	v_add_f32_e32 v212, v160, v161
	v_add_f32_e32 v214, v80, v81
	v_add_f32_e32 v215, v82, v83
	ds_read2_b64 v[88:91], v247 offset0:192 offset1:208
	ds_read_b128 v[136:139], v244 offset:3072
	ds_read_b128 v[92:95], v244 offset:3328
	ds_read_b128 v[160:163], v244 offset:11264
	ds_read_b128 v[108:111], v244 offset:11520
	ds_read_b128 v[128:131], v244 offset:19456
	ds_read_b128 v[80:83], v244 offset:19712
	ds_read_b128 v[140:143], v244 offset:27648
	ds_read_b128 v[96:99], v244 offset:27904
	ds_read_b128 v[132:135], v244 offset:35840
	ds_read_b128 v[84:87], v244 offset:36096
	s_waitcnt lgkmcnt(14)
	v_pk_mul_f32 v[210:211], v[174:175], v[166:167]
	v_pk_mul_f32 v[174:175], v[174:175], v[164:165]
	v_pk_fma_f32 v[210:211], v[172:173], v[170:171], v[210:211]
	v_pk_fma_f32 v[172:173], v[172:173], v[168:169], v[174:175]
	v_add_f32_e32 v174, v210, v211
	v_cndmask_b32_e64 v210, v213, v212, s[6:7]
	v_cndmask_b32_e64 v211, v214, v215, s[6:7]
	v_cndmask_b32_e64 v212, v212, v213, s[6:7]
	v_cndmask_b32_e64 v213, v215, v214, s[6:7]
	v_add_f32_e32 v172, v172, v173
	v_add_f32_dpp v210, v210, v212 quad_perm:[1,0,3,2] row_mask:0xf bank_mask:0xf bound_ctrl:1
	v_add_f32_dpp v211, v211, v213 quad_perm:[1,0,3,2] row_mask:0xf bank_mask:0xf bound_ctrl:1
	v_add_f32_dpp v173, v174, v174 quad_perm:[1,0,3,2] row_mask:0xf bank_mask:0xf bound_ctrl:1
	v_add_f32_dpp v172, v172, v172 quad_perm:[1,0,3,2] row_mask:0xf bank_mask:0xf bound_ctrl:1
	v_cndmask_b32_e64 v212, v210, v211, s[8:9]
	v_cndmask_b32_e64 v210, v211, v210, s[8:9]
	v_add_f32_dpp v173, v173, v173 quad_perm:[2,3,0,1] row_mask:0xf bank_mask:0xf bound_ctrl:1
	v_add_f32_dpp v174, v172, v172 quad_perm:[2,3,0,1] row_mask:0xf bank_mask:0xf bound_ctrl:1
	v_add_f32_dpp v210, v212, v210 quad_perm:[2,3,0,1] row_mask:0xf bank_mask:0xf bound_ctrl:1
	v_add_f32_dpp v172, v173, v173 row_ror:4 row_mask:0xf bank_mask:0xf bound_ctrl:1
	v_add_f32_dpp v173, v174, v174 row_ror:4 row_mask:0xf bank_mask:0xf bound_ctrl:1
	v_mov_b32_e32 v174, v177
	v_mov_b32_e32 v175, v177
	v_add_f32_dpp v210, v210, v210 row_ror:4 row_mask:0xf bank_mask:0xf bound_ctrl:1
	v_mov_b32_e32 v211, v177
	v_mov_b32_dpp v174, v172 row_ror:8 row_mask:0xf bank_mask:0xf
	v_mov_b32_dpp v175, v173 row_ror:8 row_mask:0xf bank_mask:0xf
	v_mov_b32_dpp v211, v210 row_ror:8 row_mask:0xf bank_mask:0xf
	s_and_saveexec_b64 s[78:79], s[10:11]
	v_add_f32_e32 v210, v210, v211
	ds_write_b32 v245, v210 offset:1024
	s_or_b64 exec, exec, s[78:79]
	v_pk_mul_f32 v[170:171], v[152:153], v[170:171]
	v_pk_mul_f32 v[166:167], v[154:155], v[166:167]
	v_pk_mul_f32 v[152:153], v[152:153], v[168:169]
	v_pk_mul_f32 v[154:155], v[154:155], v[164:165]
	v_pk_fma_f32 v[170:171], v[156:157], v[112:113], v[170:171] op_sel_hi:[1,0,1]
	v_pk_fma_f32 v[166:167], v[158:159], v[112:113], v[166:167] op_sel_hi:[1,0,1]
	v_pk_fma_f32 v[152:153], v[156:157], v[112:113], v[152:153] op_sel:[0,1,0]
	v_pk_fma_f32 v[112:113], v[158:159], v[112:113], v[154:155] op_sel:[0,1,0]
	v_add_f32_e32 v154, v172, v174
	v_add_f32_e32 v156, v173, v175
	v_pk_fma_f32 v[158:159], v[144:145], v[154:155], v[170:171] op_sel_hi:[1,0,1] neg_lo:[1,0,0] neg_hi:[1,0,0]
	v_pk_fma_f32 v[154:155], v[146:147], v[154:155], v[166:167] op_sel_hi:[1,0,1] neg_lo:[1,0,0] neg_hi:[1,0,0]
	v_pk_fma_f32 v[112:113], v[146:147], v[156:157], v[112:113] op_sel_hi:[1,0,1] neg_lo:[1,0,0] neg_hi:[1,0,0]
	s_waitcnt lgkmcnt(12)
	v_pk_mul_f32 v[146:147], v[150:151], v[154:155]
	v_pk_fma_f32 v[144:145], v[144:145], v[156:157], v[152:153] op_sel_hi:[1,0,1] neg_lo:[1,0,0] neg_hi:[1,0,0]
	v_pk_fma_f32 v[146:147], v[148:149], v[158:159], v[146:147]
	v_pk_mul_f32 v[150:151], v[150:151], v[112:113]
	v_add_f32_e32 v212, v146, v147
	v_pk_mul_f32 v[146:147], v[126:127], v[154:155]
	v_pk_mul_f32 v[126:127], v[126:127], v[112:113]
	v_pk_fma_f32 v[146:147], v[124:125], v[158:159], v[146:147]
	v_pk_fma_f32 v[124:125], v[124:125], v[144:145], v[126:127]
	v_add_f32_e32 v146, v146, v147
	v_add_f32_e32 v147, v124, v125
	v_pk_mul_f32 v[124:125], v[116:117], v[158:159]
	v_pk_mul_f32 v[126:127], v[118:119], v[154:155]
	v_pk_mul_f32 v[116:117], v[116:117], v[144:145]
	v_pk_mul_f32 v[112:113], v[118:119], v[112:113]
	v_pk_fma_f32 v[124:125], v[120:121], v[114:115], v[124:125] op_sel_hi:[1,0,1]
	v_pk_fma_f32 v[126:127], v[122:123], v[114:115], v[126:127] op_sel_hi:[1,0,1]
	v_pk_fma_f32 v[116:117], v[120:121], v[114:115], v[116:117] op_sel:[0,1,0]
	v_pk_fma_f32 v[112:113], v[122:123], v[114:115], v[112:113] op_sel:[0,1,0]
	v_add_f32_dpp v114, v146, v146 quad_perm:[1,0,3,2] row_mask:0xf bank_mask:0xf bound_ctrl:1
	v_add_f32_dpp v115, v147, v147 quad_perm:[1,0,3,2] row_mask:0xf bank_mask:0xf bound_ctrl:1
	v_pk_fma_f32 v[148:149], v[148:149], v[144:145], v[150:151]
	v_add_f32_dpp v114, v114, v114 quad_perm:[2,3,0,1] row_mask:0xf bank_mask:0xf bound_ctrl:1
	v_add_f32_dpp v115, v115, v115 quad_perm:[2,3,0,1] row_mask:0xf bank_mask:0xf bound_ctrl:1
	v_add_f32_e32 v213, v148, v149
	v_add_f32_dpp v114, v114, v114 row_ror:4 row_mask:0xf bank_mask:0xf bound_ctrl:1
	v_add_f32_dpp v115, v115, v115 row_ror:4 row_mask:0xf bank_mask:0xf bound_ctrl:1
	s_nop 0
	v_add_f32_dpp v114, v114, v114 row_ror:8 row_mask:0xf bank_mask:0xf bound_ctrl:1
	v_add_f32_dpp v118, v115, v115 row_ror:8 row_mask:0xf bank_mask:0xf bound_ctrl:1
	v_pk_fma_f32 v[170:171], v[102:103], v[114:115], v[126:127] op_sel_hi:[1,0,1] neg_lo:[1,0,0] neg_hi:[1,0,0]
	v_pk_fma_f32 v[168:169], v[102:103], v[118:119], v[112:113] op_sel_hi:[1,0,1] neg_lo:[1,0,0] neg_hi:[1,0,0]
	v_pk_fma_f32 v[174:175], v[100:101], v[114:115], v[124:125] op_sel_hi:[1,0,1] neg_lo:[1,0,0] neg_hi:[1,0,0]
	v_pk_fma_f32 v[172:173], v[100:101], v[118:119], v[116:117] op_sel_hi:[1,0,1] neg_lo:[1,0,0] neg_hi:[1,0,0]
	s_waitcnt lgkmcnt(11)
	v_pk_mul_f32 v[100:101], v[106:107], v[170:171]
	v_pk_mul_f32 v[102:103], v[106:107], v[168:169]
	v_pk_fma_f32 v[100:101], v[104:105], v[174:175], v[100:101]
	v_pk_fma_f32 v[102:103], v[104:105], v[172:173], v[102:103]
	v_add_f32_e32 v214, v100, v101
	v_add_f32_e32 v215, v102, v103
	ds_read2_b64 v[112:115], v247 offset0:224 offset1:240
	ds_read_b128 v[152:155], v244 offset:3584
	ds_read_b128 v[116:119], v244 offset:3840
	ds_read_b128 v[164:167], v244 offset:11776
	ds_read_b128 v[124:127], v244 offset:12032
	ds_read_b128 v[144:147], v244 offset:19968
	ds_read_b128 v[100:103], v244 offset:20224
	ds_read_b128 v[156:159], v244 offset:28160
	ds_read_b128 v[120:123], v244 offset:28416
	ds_read_b128 v[148:151], v244 offset:36352
	ds_read_b128 v[104:107], v244 offset:36608
	s_waitcnt lgkmcnt(14)
	v_pk_mul_f32 v[210:211], v[162:163], v[170:171]
	v_pk_mul_f32 v[162:163], v[162:163], v[168:169]
	v_pk_fma_f32 v[210:211], v[160:161], v[174:175], v[210:211]
	v_pk_fma_f32 v[160:161], v[160:161], v[172:173], v[162:163]
	v_add_f32_e32 v162, v210, v211
	v_cndmask_b32_e64 v210, v212, v213, s[6:7]
	v_cndmask_b32_e64 v211, v214, v215, s[6:7]
	v_cndmask_b32_e64 v212, v213, v212, s[6:7]
	v_cndmask_b32_e64 v213, v215, v214, s[6:7]
	v_add_f32_e32 v160, v160, v161
	v_add_f32_dpp v210, v210, v212 quad_perm:[1,0,3,2] row_mask:0xf bank_mask:0xf bound_ctrl:1
	v_add_f32_dpp v211, v211, v213 quad_perm:[1,0,3,2] row_mask:0xf bank_mask:0xf bound_ctrl:1
	v_add_f32_dpp v161, v162, v162 quad_perm:[1,0,3,2] row_mask:0xf bank_mask:0xf bound_ctrl:1
	v_add_f32_dpp v160, v160, v160 quad_perm:[1,0,3,2] row_mask:0xf bank_mask:0xf bound_ctrl:1
	v_cndmask_b32_e64 v212, v210, v211, s[8:9]
	v_cndmask_b32_e64 v210, v211, v210, s[8:9]
	v_add_f32_dpp v161, v161, v161 quad_perm:[2,3,0,1] row_mask:0xf bank_mask:0xf bound_ctrl:1
	v_add_f32_dpp v162, v160, v160 quad_perm:[2,3,0,1] row_mask:0xf bank_mask:0xf bound_ctrl:1
	v_add_f32_dpp v210, v212, v210 quad_perm:[2,3,0,1] row_mask:0xf bank_mask:0xf bound_ctrl:1
	v_add_f32_dpp v160, v161, v161 row_ror:4 row_mask:0xf bank_mask:0xf bound_ctrl:1
	v_add_f32_dpp v161, v162, v162 row_ror:4 row_mask:0xf bank_mask:0xf bound_ctrl:1
	v_mov_b32_e32 v162, 0
	v_mov_b32_e32 v163, 0
	v_add_f32_dpp v210, v210, v210 row_ror:4 row_mask:0xf bank_mask:0xf bound_ctrl:1
	v_mov_b32_e32 v211, 0
	v_mov_b32_dpp v162, v160 row_ror:8 row_mask:0xf bank_mask:0xf
	v_mov_b32_dpp v163, v161 row_ror:8 row_mask:0xf bank_mask:0xf
	v_mov_b32_dpp v211, v210 row_ror:8 row_mask:0xf bank_mask:0xf
	s_and_saveexec_b64 s[78:79], s[10:11]
	v_add_f32_e32 v210, v210, v211
	ds_write_b32 v245, v210 offset:1280
	s_or_b64 exec, exec, s[78:79]
	v_pk_mul_f32 v[174:175], v[136:137], v[174:175]
	v_pk_mul_f32 v[170:171], v[138:139], v[170:171]
	v_pk_mul_f32 v[136:137], v[136:137], v[172:173]
	v_pk_mul_f32 v[138:139], v[138:139], v[168:169]
	v_pk_fma_f32 v[174:175], v[140:141], v[88:89], v[174:175] op_sel_hi:[1,0,1]
	v_pk_fma_f32 v[170:171], v[142:143], v[88:89], v[170:171] op_sel_hi:[1,0,1]
	v_pk_fma_f32 v[136:137], v[140:141], v[88:89], v[136:137] op_sel:[0,1,0]
	v_pk_fma_f32 v[88:89], v[142:143], v[88:89], v[138:139] op_sel:[0,1,0]
	v_add_f32_e32 v138, v160, v162
	v_add_f32_e32 v140, v161, v163
	v_pk_fma_f32 v[142:143], v[128:129], v[138:139], v[174:175] op_sel_hi:[1,0,1] neg_lo:[1,0,0] neg_hi:[1,0,0]
	v_pk_fma_f32 v[138:139], v[130:131], v[138:139], v[170:171] op_sel_hi:[1,0,1] neg_lo:[1,0,0] neg_hi:[1,0,0]
	v_pk_fma_f32 v[88:89], v[130:131], v[140:141], v[88:89] op_sel_hi:[1,0,1] neg_lo:[1,0,0] neg_hi:[1,0,0]
	s_waitcnt lgkmcnt(12)
	v_pk_mul_f32 v[130:131], v[134:135], v[138:139]
	v_pk_fma_f32 v[128:129], v[128:129], v[140:141], v[136:137] op_sel_hi:[1,0,1] neg_lo:[1,0,0] neg_hi:[1,0,0]
	v_pk_fma_f32 v[130:131], v[132:133], v[142:143], v[130:131]
	v_pk_mul_f32 v[134:135], v[134:135], v[88:89]
	s_nop 0
	v_pk_fma_f32 v[132:133], v[132:133], v[128:129], v[134:135]
	v_add_f32_e32 v134, v130, v131
	v_pk_mul_f32 v[130:131], v[110:111], v[138:139]
	v_pk_mul_f32 v[110:111], v[110:111], v[88:89]
	v_pk_fma_f32 v[130:131], v[108:109], v[142:143], v[130:131]
	v_pk_fma_f32 v[108:109], v[108:109], v[128:129], v[110:111]
	v_add_f32_e32 v130, v130, v131
	v_add_f32_e32 v131, v108, v109
	v_pk_mul_f32 v[88:89], v[94:95], v[88:89]
	v_pk_mul_f32 v[110:111], v[94:95], v[138:139]
	v_pk_fma_f32 v[94:95], v[98:99], v[90:91], v[88:89] op_sel:[0,1,0]
	v_add_f32_dpp v88, v130, v130 quad_perm:[1,0,3,2] row_mask:0xf bank_mask:0xf bound_ctrl:1
	v_add_f32_dpp v89, v131, v131 quad_perm:[1,0,3,2] row_mask:0xf bank_mask:0xf bound_ctrl:1
	v_pk_mul_f32 v[108:109], v[92:93], v[142:143]
	v_add_f32_dpp v88, v88, v88 quad_perm:[2,3,0,1] row_mask:0xf bank_mask:0xf bound_ctrl:1
	v_add_f32_dpp v89, v89, v89 quad_perm:[2,3,0,1] row_mask:0xf bank_mask:0xf bound_ctrl:1
	v_pk_mul_f32 v[92:93], v[92:93], v[128:129]
	v_add_f32_dpp v88, v88, v88 row_ror:4 row_mask:0xf bank_mask:0xf bound_ctrl:1
	v_add_f32_dpp v89, v89, v89 row_ror:4 row_mask:0xf bank_mask:0xf bound_ctrl:1
	v_pk_fma_f32 v[108:109], v[96:97], v[90:91], v[108:109] op_sel_hi:[1,0,1]
	v_pk_fma_f32 v[110:111], v[98:99], v[90:91], v[110:111] op_sel_hi:[1,0,1]
	v_pk_fma_f32 v[96:97], v[96:97], v[90:91], v[92:93] op_sel:[0,1,0]
	v_add_f32_dpp v88, v88, v88 row_ror:8 row_mask:0xf bank_mask:0xf bound_ctrl:1
	v_add_f32_dpp v98, v89, v89 row_ror:8 row_mask:0xf bank_mask:0xf bound_ctrl:1
	v_pk_fma_f32 v[92:93], v[80:81], v[88:89], v[108:109] op_sel_hi:[1,0,1] neg_lo:[1,0,0] neg_hi:[1,0,0]
	v_pk_fma_f32 v[88:89], v[82:83], v[88:89], v[110:111] op_sel_hi:[1,0,1] neg_lo:[1,0,0] neg_hi:[1,0,0]
	v_pk_fma_f32 v[90:91], v[80:81], v[98:99], v[96:97] op_sel_hi:[1,0,1] neg_lo:[1,0,0] neg_hi:[1,0,0]
	v_pk_fma_f32 v[80:81], v[82:83], v[98:99], v[94:95] op_sel_hi:[1,0,1] neg_lo:[1,0,0] neg_hi:[1,0,0]
	s_waitcnt lgkmcnt(11)
	v_pk_mul_f32 v[82:83], v[86:87], v[88:89]
	v_pk_mul_f32 v[86:87], v[86:87], v[80:81]
	v_pk_fma_f32 v[82:83], v[84:85], v[92:93], v[82:83]
	v_pk_fma_f32 v[84:85], v[84:85], v[90:91], v[86:87]
	v_add_f32_e32 v86, v82, v83
	v_add_f32_e32 v87, v84, v85
	v_add_f32_e32 v132, v132, v133
	s_waitcnt lgkmcnt(7)
	v_pk_mul_f32 v[82:83], v[166:167], v[88:89]
	v_pk_mul_f32 v[84:85], v[166:167], v[80:81]
	v_pk_fma_f32 v[82:83], v[164:165], v[92:93], v[82:83]
	v_pk_fma_f32 v[84:85], v[164:165], v[90:91], v[84:85]
	v_cndmask_b32_e64 v94, v134, v132, s[6:7]
	v_cndmask_b32_e64 v95, v86, v87, s[6:7]
	v_cndmask_b32_e64 v96, v132, v134, s[6:7]
	v_cndmask_b32_e64 v86, v87, v86, s[6:7]
	v_add_f32_e32 v82, v82, v83
	v_add_f32_e32 v83, v84, v85
	v_add_f32_dpp v87, v94, v96 quad_perm:[1,0,3,2] row_mask:0xf bank_mask:0xf bound_ctrl:1
	v_add_f32_dpp v86, v95, v86 quad_perm:[1,0,3,2] row_mask:0xf bank_mask:0xf bound_ctrl:1
	v_add_f32_dpp v82, v82, v82 quad_perm:[1,0,3,2] row_mask:0xf bank_mask:0xf bound_ctrl:1
	v_add_f32_dpp v83, v83, v83 quad_perm:[1,0,3,2] row_mask:0xf bank_mask:0xf bound_ctrl:1
	v_cndmask_b32_e64 v94, v87, v86, s[8:9]
	v_cndmask_b32_e64 v86, v86, v87, s[8:9]
	v_add_f32_dpp v82, v82, v82 quad_perm:[2,3,0,1] row_mask:0xf bank_mask:0xf bound_ctrl:1
	v_add_f32_dpp v83, v83, v83 quad_perm:[2,3,0,1] row_mask:0xf bank_mask:0xf bound_ctrl:1
	v_add_f32_dpp v86, v94, v86 quad_perm:[2,3,0,1] row_mask:0xf bank_mask:0xf bound_ctrl:1
	v_add_f32_dpp v82, v82, v82 row_ror:4 row_mask:0xf bank_mask:0xf bound_ctrl:1
	v_add_f32_dpp v83, v83, v83 row_ror:4 row_mask:0xf bank_mask:0xf bound_ctrl:1
	v_mov_b32_e32 v84, 0
	v_mov_b32_e32 v85, 0
	v_add_f32_dpp v86, v86, v86 row_ror:4 row_mask:0xf bank_mask:0xf bound_ctrl:1
	v_mov_b32_e32 v87, 0
	v_mov_b32_dpp v84, v82 row_ror:8 row_mask:0xf bank_mask:0xf
	v_mov_b32_dpp v85, v83 row_ror:8 row_mask:0xf bank_mask:0xf
	v_mov_b32_dpp v87, v86 row_ror:8 row_mask:0xf bank_mask:0xf
	s_and_saveexec_b64 s[78:79], s[10:11]
	v_add_f32_e32 v86, v86, v87
	ds_write_b32 v245, v86 offset:1536
	s_or_b64 exec, exec, s[78:79]
	v_pk_mul_f32 v[86:87], v[152:153], v[92:93]
	v_pk_mul_f32 v[88:89], v[154:155], v[88:89]
	v_pk_mul_f32 v[80:81], v[154:155], v[80:81]
	s_waitcnt lgkmcnt(3)
	v_pk_fma_f32 v[86:87], v[156:157], v[112:113], v[86:87] op_sel_hi:[1,0,1]
	v_pk_fma_f32 v[88:89], v[158:159], v[112:113], v[88:89] op_sel_hi:[1,0,1]
	v_pk_mul_f32 v[90:91], v[152:153], v[90:91]
	v_pk_fma_f32 v[80:81], v[158:159], v[112:113], v[80:81] op_sel:[0,1,0]
	v_add_f32_e32 v82, v82, v84
	v_add_f32_e32 v84, v83, v85
	v_pk_fma_f32 v[90:91], v[156:157], v[112:113], v[90:91] op_sel:[0,1,0]
	v_pk_fma_f32 v[86:87], v[144:145], v[82:83], v[86:87] op_sel_hi:[1,0,1] neg_lo:[1,0,0] neg_hi:[1,0,0]
	v_pk_fma_f32 v[82:83], v[146:147], v[82:83], v[88:89] op_sel_hi:[1,0,1] neg_lo:[1,0,0] neg_hi:[1,0,0]
	v_pk_fma_f32 v[80:81], v[146:147], v[84:85], v[80:81] op_sel_hi:[1,0,1] neg_lo:[1,0,0] neg_hi:[1,0,0]
	v_pk_fma_f32 v[88:89], v[144:145], v[84:85], v[90:91] op_sel_hi:[1,0,1] neg_lo:[1,0,0] neg_hi:[1,0,0]
	s_waitcnt lgkmcnt(1)
	v_pk_mul_f32 v[84:85], v[150:151], v[82:83]
	v_pk_mul_f32 v[90:91], v[150:151], v[80:81]
	v_pk_fma_f32 v[84:85], v[148:149], v[86:87], v[84:85]
	v_pk_fma_f32 v[90:91], v[148:149], v[88:89], v[90:91]
	v_add_f32_e32 v96, v84, v85
	v_add_f32_e32 v97, v90, v91
	v_pk_mul_f32 v[84:85], v[126:127], v[82:83]
	v_pk_mul_f32 v[90:91], v[126:127], v[80:81]
	v_pk_fma_f32 v[84:85], v[124:125], v[86:87], v[84:85]
	v_pk_fma_f32 v[90:91], v[124:125], v[88:89], v[90:91]
	v_add_f32_e32 v92, v84, v85
	v_add_f32_e32 v90, v90, v91
	v_pk_mul_f32 v[84:85], v[116:117], v[86:87]
	v_pk_mul_f32 v[86:87], v[116:117], v[88:89]
	v_add_f32_dpp v88, v92, v92 quad_perm:[1,0,3,2] row_mask:0xf bank_mask:0xf bound_ctrl:1
	v_add_f32_dpp v89, v90, v90 quad_perm:[1,0,3,2] row_mask:0xf bank_mask:0xf bound_ctrl:1
	v_pk_mul_f32 v[82:83], v[118:119], v[82:83]
	v_add_f32_dpp v88, v88, v88 quad_perm:[2,3,0,1] row_mask:0xf bank_mask:0xf bound_ctrl:1
	v_add_f32_dpp v89, v89, v89 quad_perm:[2,3,0,1] row_mask:0xf bank_mask:0xf bound_ctrl:1
	v_pk_mul_f32 v[80:81], v[118:119], v[80:81]
	v_add_f32_dpp v88, v88, v88 row_ror:4 row_mask:0xf bank_mask:0xf bound_ctrl:1
	v_add_f32_dpp v89, v89, v89 row_ror:4 row_mask:0xf bank_mask:0xf bound_ctrl:1
	v_pk_fma_f32 v[84:85], v[120:121], v[114:115], v[84:85] op_sel_hi:[1,0,1]
	v_pk_fma_f32 v[82:83], v[122:123], v[114:115], v[82:83] op_sel_hi:[1,0,1]
	v_pk_fma_f32 v[86:87], v[120:121], v[114:115], v[86:87] op_sel:[0,1,0]
	v_pk_fma_f32 v[80:81], v[122:123], v[114:115], v[80:81] op_sel:[0,1,0]
	v_add_f32_dpp v90, v88, v88 row_ror:8 row_mask:0xf bank_mask:0xf bound_ctrl:1
	v_add_f32_dpp v94, v89, v89 row_ror:8 row_mask:0xf bank_mask:0xf bound_ctrl:1
	v_pk_fma_f32 v[88:89], v[100:101], v[90:91], v[84:85] op_sel_hi:[1,0,1] neg_lo:[1,0,0] neg_hi:[1,0,0]
	v_pk_fma_f32 v[90:91], v[102:103], v[90:91], v[82:83] op_sel_hi:[1,0,1] neg_lo:[1,0,0] neg_hi:[1,0,0]
	v_pk_fma_f32 v[92:93], v[100:101], v[94:95], v[86:87] op_sel_hi:[1,0,1] neg_lo:[1,0,0] neg_hi:[1,0,0]
	v_pk_fma_f32 v[94:95], v[102:103], v[94:95], v[80:81] op_sel_hi:[1,0,1] neg_lo:[1,0,0] neg_hi:[1,0,0]
	s_waitcnt lgkmcnt(0)
	v_pk_mul_f32 v[80:81], v[106:107], v[90:91]
	v_pk_mul_f32 v[82:83], v[106:107], v[94:95]
	v_pk_fma_f32 v[80:81], v[104:105], v[88:89], v[80:81]
	v_pk_fma_f32 v[82:83], v[104:105], v[92:93], v[82:83]
	v_add_f32_e32 v80, v80, v81
	v_add_f32_e32 v81, v82, v83
	v_cndmask_b32_e64 v82, v96, v97, s[6:7]
	v_cndmask_b32_e64 v83, v80, v81, s[6:7]
	v_cndmask_b32_e64 v84, v97, v96, s[6:7]
	v_cndmask_b32_e64 v80, v81, v80, s[6:7]
	s_nop 0
	v_add_f32_dpp v81, v82, v84 quad_perm:[1,0,3,2] row_mask:0xf bank_mask:0xf bound_ctrl:1
	v_add_f32_dpp v80, v83, v80 quad_perm:[1,0,3,2] row_mask:0xf bank_mask:0xf bound_ctrl:1
	v_cndmask_b32_e64 v82, v81, v80, s[8:9]
	v_cndmask_b32_e64 v80, v80, v81, s[8:9]
	v_mov_b32_e32 v81, 0
	s_nop 0
	v_add_f32_dpp v80, v82, v80 quad_perm:[2,3,0,1] row_mask:0xf bank_mask:0xf bound_ctrl:1
	s_nop 1
	v_add_f32_dpp v80, v80, v80 row_ror:4 row_mask:0xf bank_mask:0xf bound_ctrl:1
	s_nop 1
	v_mov_b32_dpp v81, v80 row_ror:8 row_mask:0xf bank_mask:0xf
	s_and_saveexec_b64 s[78:79], s[10:11]
	v_add3_u32 v82, v176, v239, v197
	v_add_f32_e32 v80, v80, v81
	ds_write_b32 v82, v80 offset:1792
	s_or_b64 exec, exec, s[78:79]
	s_setprio 0
	s_ashr_i32 s28, s24, 5
	s_add_i32 s29, s24, 0xffffff00
	s_not_b32 s28, s28
	s_lshr_b32 s29, s29, 5
	s_cmpk_lt_i32 s24, 0x100
	s_cselect_b32 s28, s28, s29
	s_ashr_i32 s29, s28, 31
	s_lshl_b32 s24, s24, 5
	s_lshl_b64 s[28:29], s[28:29], 10
	s_and_b32 s24, s24, 0x3e0
	s_or_b32 s24, s28, s24
	v_mov_b32_e32 v81, s29
	v_or_b32_e32 v80, s24, v192
	v_lshlrev_b64 v[80:81], 8, v[80:81]
	v_lshl_add_u64 v[80:81], v[198:199], 0, v[80:81]
	global_store_dwordx4 v[80:81], v[88:91], off
	global_store_dwordx4 v[80:81], v[92:95], off offset:256
	s_add_i32 s24, s70, s5
	s_cmpk_gt_i32 s24, 0x10ff
	v_add_u32_e32 v168, 0xa800, v246
	s_cbranch_scc0 .LBB0_328

.LBB0_328:
	s_setprio 0
	ds_read2_b64 v[80:83], v168 offset1:16
	ds_read_b128 v[84:87], v244 offset:37120
	ds_read_b128 v[88:91], v244 offset:36864
	ds_read_b128 v[100:103], v244 offset:28928
	ds_read_b128 v[120:123], v244 offset:28672
	ds_read_b128 v[124:127], v244 offset:20736
	ds_read_b128 v[128:131], v244 offset:20480
	ds_read_b128 v[132:135], v244 offset:12544
	ds_read_b128 v[152:155], v244 offset:12288
	ds_read_b128 v[156:159], v244 offset:4352
	ds_read_b128 v[160:163], v244 offset:4096
	ds_read2_b64 v[104:107], v168 offset0:32 offset1:48
	ds_read_b128 v[144:147], v244 offset:4608
	ds_read_b128 v[108:111], v244 offset:4864
	ds_read_b128 v[164:167], v244 offset:12800
	ds_read_b128 v[116:119], v244 offset:13056
	ds_read_b128 v[136:139], v244 offset:20992
	ds_read_b128 v[92:95], v244 offset:21248
	ds_read_b128 v[148:151], v244 offset:29184
	ds_read_b128 v[112:115], v244 offset:29440
	ds_read_b128 v[140:143], v244 offset:37376
	ds_read_b128 v[96:99], v244 offset:37632
	s_waitcnt lgkmcnt(13)
	v_pk_mul_f32 v[170:171], v[74:75], v[154:155]
	v_pk_mul_f32 v[154:155], v[78:79], v[154:155]
	v_pk_fma_f32 v[170:171], v[72:73], v[152:153], v[170:171]
	v_pk_fma_f32 v[152:153], v[76:77], v[152:153], v[154:155]
	v_add_f32_e32 v154, v170, v171
	v_add_f32_e32 v152, v152, v153
	s_waitcnt lgkmcnt(11)
	v_pk_mul_f32 v[76:77], v[76:77], v[160:161]
	v_add_f32_dpp v153, v154, v154 quad_perm:[1,0,3,2] row_mask:0xf bank_mask:0xf bound_ctrl:1
	v_add_f32_dpp v152, v152, v152 quad_perm:[1,0,3,2] row_mask:0xf bank_mask:0xf bound_ctrl:1
	v_pk_mul_f32 v[72:73], v[72:73], v[160:161]
	v_add_f32_dpp v153, v153, v153 quad_perm:[2,3,0,1] row_mask:0xf bank_mask:0xf bound_ctrl:1
	v_add_f32_dpp v152, v152, v152 quad_perm:[2,3,0,1] row_mask:0xf bank_mask:0xf bound_ctrl:1
	v_pk_mul_f32 v[74:75], v[74:75], v[162:163]
	v_add_f32_dpp v154, v153, v153 row_ror:4 row_mask:0xf bank_mask:0xf bound_ctrl:1
	v_add_f32_dpp v152, v152, v152 row_ror:4 row_mask:0xf bank_mask:0xf bound_ctrl:1
	v_pk_fma_f32 v[76:77], v[80:81], v[120:121], v[76:77] op_sel:[1,0,0]
	v_pk_mul_f32 v[78:79], v[78:79], v[162:163]
	v_pk_fma_f32 v[72:73], v[80:81], v[120:121], v[72:73] op_sel_hi:[0,1,1]
	v_add_f32_dpp v120, v154, v154 row_ror:8 row_mask:0xf bank_mask:0xf bound_ctrl:1
	v_pk_fma_f32 v[74:75], v[80:81], v[122:123], v[74:75] op_sel_hi:[0,1,1]
	v_add_f32_dpp v152, v152, v152 row_ror:8 row_mask:0xf bank_mask:0xf bound_ctrl:1
	v_pk_fma_f32 v[78:79], v[80:81], v[122:123], v[78:79] op_sel:[1,0,0]
	v_pk_fma_f32 v[74:75], v[130:131], v[120:121], v[74:75] op_sel_hi:[1,0,1] neg_lo:[1,0,0] neg_hi:[1,0,0]
	v_pk_fma_f32 v[78:79], v[130:131], v[152:153], v[78:79] op_sel_hi:[1,0,1] neg_lo:[1,0,0] neg_hi:[1,0,0]
	v_pk_fma_f32 v[72:73], v[128:129], v[120:121], v[72:73] op_sel_hi:[1,0,1] neg_lo:[1,0,0] neg_hi:[1,0,0]
	v_pk_mul_f32 v[80:81], v[90:91], v[74:75]
	v_pk_fma_f32 v[76:77], v[128:129], v[152:153], v[76:77] op_sel_hi:[1,0,1] neg_lo:[1,0,0] neg_hi:[1,0,0]
	v_pk_mul_f32 v[152:153], v[90:91], v[78:79]
	v_pk_fma_f32 v[80:81], v[88:89], v[72:73], v[80:81]
	v_pk_fma_f32 v[152:153], v[88:89], v[76:77], v[152:153]
	v_add_f32_e32 v172, v80, v81
	v_pk_mul_f32 v[80:81], v[134:135], v[74:75]
	v_pk_mul_f32 v[88:89], v[134:135], v[78:79]
	v_pk_fma_f32 v[80:81], v[132:133], v[72:73], v[80:81]
	v_pk_fma_f32 v[88:89], v[132:133], v[76:77], v[88:89]
	v_add_f32_e32 v80, v80, v81
	v_add_f32_e32 v81, v88, v89
	v_pk_mul_f32 v[72:73], v[156:157], v[72:73]
	v_add_f32_dpp v80, v80, v80 quad_perm:[1,0,3,2] row_mask:0xf bank_mask:0xf bound_ctrl:1
	v_add_f32_dpp v81, v81, v81 quad_perm:[1,0,3,2] row_mask:0xf bank_mask:0xf bound_ctrl:1
	v_pk_mul_f32 v[74:75], v[158:159], v[74:75]
	v_add_f32_dpp v80, v80, v80 quad_perm:[2,3,0,1] row_mask:0xf bank_mask:0xf bound_ctrl:1
	v_add_f32_dpp v81, v81, v81 quad_perm:[2,3,0,1] row_mask:0xf bank_mask:0xf bound_ctrl:1
	v_pk_mul_f32 v[76:77], v[156:157], v[76:77]
	v_pk_mul_f32 v[78:79], v[158:159], v[78:79]
	v_add_f32_dpp v80, v80, v80 row_ror:4 row_mask:0xf bank_mask:0xf bound_ctrl:1
	v_add_f32_dpp v81, v81, v81 row_ror:4 row_mask:0xf bank_mask:0xf bound_ctrl:1
	v_pk_fma_f32 v[72:73], v[82:83], v[100:101], v[72:73] op_sel_hi:[0,1,1]
	v_pk_fma_f32 v[74:75], v[82:83], v[102:103], v[74:75] op_sel_hi:[0,1,1]
	v_pk_fma_f32 v[76:77], v[82:83], v[100:101], v[76:77] op_sel:[1,0,0]
	v_pk_fma_f32 v[78:79], v[82:83], v[102:103], v[78:79] op_sel:[1,0,0]
	v_add_f32_dpp v80, v80, v80 row_ror:8 row_mask:0xf bank_mask:0xf bound_ctrl:1
	v_add_f32_dpp v82, v81, v81 row_ror:8 row_mask:0xf bank_mask:0xf bound_ctrl:1
	v_pk_fma_f32 v[158:159], v[126:127], v[80:81], v[74:75] op_sel_hi:[1,0,1] neg_lo:[1,0,0] neg_hi:[1,0,0]
	v_pk_fma_f32 v[156:157], v[126:127], v[82:83], v[78:79] op_sel_hi:[1,0,1] neg_lo:[1,0,0] neg_hi:[1,0,0]
	v_pk_fma_f32 v[162:163], v[124:125], v[80:81], v[72:73] op_sel_hi:[1,0,1] neg_lo:[1,0,0] neg_hi:[1,0,0]
	v_pk_fma_f32 v[160:161], v[124:125], v[82:83], v[76:77] op_sel_hi:[1,0,1] neg_lo:[1,0,0] neg_hi:[1,0,0]
	v_pk_mul_f32 v[72:73], v[86:87], v[158:159]
	v_pk_mul_f32 v[74:75], v[86:87], v[156:157]
	v_add_f32_e32 v169, v152, v153
	v_pk_fma_f32 v[72:73], v[84:85], v[162:163], v[72:73]
	v_pk_fma_f32 v[74:75], v[84:85], v[160:161], v[74:75]
	v_add_f32_e32 v173, v72, v73
	v_add_f32_e32 v174, v74, v75
	ds_read2_b64 v[80:83], v168 offset0:64 offset1:80
	ds_read_b128 v[128:131], v244 offset:5120
	ds_read_b128 v[84:87], v244 offset:5376
	ds_read_b128 v[152:155], v244 offset:13312
	ds_read_b128 v[100:103], v244 offset:13568
	ds_read_b128 v[120:123], v244 offset:21504
	ds_read_b128 v[72:75], v244 offset:21760
	ds_read_b128 v[132:135], v244 offset:29696
	ds_read_b128 v[88:91], v244 offset:29952
	ds_read_b128 v[124:127], v244 offset:37888
	ds_read_b128 v[76:79], v244 offset:38144
	s_waitcnt lgkmcnt(14)
	v_pk_mul_f32 v[170:171], v[166:167], v[158:159]
	v_pk_mul_f32 v[166:167], v[166:167], v[156:157]
	v_pk_fma_f32 v[170:171], v[164:165], v[162:163], v[170:171]
	v_pk_fma_f32 v[164:165], v[164:165], v[160:161], v[166:167]
	v_add_f32_e32 v166, v170, v171
	v_cndmask_b32_e64 v170, v172, v169, s[6:7]
	v_cndmask_b32_e64 v171, v173, v174, s[6:7]
	v_cndmask_b32_e64 v169, v169, v172, s[6:7]
	v_cndmask_b32_e64 v172, v174, v173, s[6:7]
	v_add_f32_e32 v164, v164, v165
	v_add_f32_dpp v169, v170, v169 quad_perm:[1,0,3,2] row_mask:0xf bank_mask:0xf bound_ctrl:1
	v_add_f32_dpp v170, v171, v172 quad_perm:[1,0,3,2] row_mask:0xf bank_mask:0xf bound_ctrl:1
	v_add_f32_dpp v165, v166, v166 quad_perm:[1,0,3,2] row_mask:0xf bank_mask:0xf bound_ctrl:1
	v_add_f32_dpp v164, v164, v164 quad_perm:[1,0,3,2] row_mask:0xf bank_mask:0xf bound_ctrl:1
	v_cndmask_b32_e64 v171, v169, v170, s[8:9]
	v_cndmask_b32_e64 v169, v170, v169, s[8:9]
	v_add_f32_dpp v165, v165, v165 quad_perm:[2,3,0,1] row_mask:0xf bank_mask:0xf bound_ctrl:1
	v_add_f32_dpp v166, v164, v164 quad_perm:[2,3,0,1] row_mask:0xf bank_mask:0xf bound_ctrl:1
	v_add_f32_dpp v169, v171, v169 quad_perm:[2,3,0,1] row_mask:0xf bank_mask:0xf bound_ctrl:1
	v_add_f32_dpp v164, v165, v165 row_ror:4 row_mask:0xf bank_mask:0xf bound_ctrl:1
	v_add_f32_dpp v165, v166, v166 row_ror:4 row_mask:0xf bank_mask:0xf bound_ctrl:1
	v_mov_b32_e32 v166, v177
	v_mov_b32_e32 v167, v177
	v_add_f32_dpp v169, v169, v169 row_ror:4 row_mask:0xf bank_mask:0xf bound_ctrl:1
	v_mov_b32_e32 v170, v177
	v_mov_b32_dpp v166, v164 row_ror:8 row_mask:0xf bank_mask:0xf
	v_mov_b32_dpp v167, v165 row_ror:8 row_mask:0xf bank_mask:0xf
	v_mov_b32_dpp v170, v169 row_ror:8 row_mask:0xf bank_mask:0xf
	s_and_saveexec_b64 s[78:79], s[10:11]
	v_add_f32_e32 v169, v169, v170
	ds_write_b32 v245, v169 offset:2048
	s_or_b64 exec, exec, s[78:79]
	v_pk_mul_f32 v[162:163], v[144:145], v[162:163]
	v_pk_mul_f32 v[158:159], v[146:147], v[158:159]
	v_pk_mul_f32 v[144:145], v[144:145], v[160:161]
	v_pk_mul_f32 v[146:147], v[146:147], v[156:157]
	v_pk_fma_f32 v[162:163], v[148:149], v[104:105], v[162:163] op_sel_hi:[1,0,1]
	v_pk_fma_f32 v[158:159], v[150:151], v[104:105], v[158:159] op_sel_hi:[1,0,1]
	v_pk_fma_f32 v[144:145], v[148:149], v[104:105], v[144:145] op_sel:[0,1,0]
	v_pk_fma_f32 v[104:105], v[150:151], v[104:105], v[146:147] op_sel:[0,1,0]
	v_add_f32_e32 v146, v164, v166
	v_add_f32_e32 v148, v165, v167
	v_pk_fma_f32 v[150:151], v[136:137], v[146:147], v[162:163] op_sel_hi:[1,0,1] neg_lo:[1,0,0] neg_hi:[1,0,0]
	v_pk_fma_f32 v[146:147], v[138:139], v[146:147], v[158:159] op_sel_hi:[1,0,1] neg_lo:[1,0,0] neg_hi:[1,0,0]
	v_pk_fma_f32 v[104:105], v[138:139], v[148:149], v[104:105] op_sel_hi:[1,0,1] neg_lo:[1,0,0] neg_hi:[1,0,0]
	s_waitcnt lgkmcnt(12)
	v_pk_mul_f32 v[138:139], v[142:143], v[146:147]
	v_pk_fma_f32 v[136:137], v[136:137], v[148:149], v[144:145] op_sel_hi:[1,0,1] neg_lo:[1,0,0] neg_hi:[1,0,0]
	v_pk_fma_f32 v[138:139], v[140:141], v[150:151], v[138:139]
	v_pk_mul_f32 v[142:143], v[142:143], v[104:105]
	v_add_f32_e32 v169, v138, v139
	v_pk_mul_f32 v[138:139], v[118:119], v[146:147]
	v_pk_mul_f32 v[118:119], v[118:119], v[104:105]
	v_pk_fma_f32 v[138:139], v[116:117], v[150:151], v[138:139]
	v_pk_fma_f32 v[116:117], v[116:117], v[136:137], v[118:119]
	v_add_f32_e32 v138, v138, v139
	v_add_f32_e32 v139, v116, v117
	v_pk_mul_f32 v[116:117], v[108:109], v[150:151]
	v_pk_mul_f32 v[118:119], v[110:111], v[146:147]
	v_pk_mul_f32 v[108:109], v[108:109], v[136:137]
	v_pk_mul_f32 v[104:105], v[110:111], v[104:105]
	v_pk_fma_f32 v[116:117], v[112:113], v[106:107], v[116:117] op_sel_hi:[1,0,1]
	v_pk_fma_f32 v[118:119], v[114:115], v[106:107], v[118:119] op_sel_hi:[1,0,1]
	v_pk_fma_f32 v[108:109], v[112:113], v[106:107], v[108:109] op_sel:[0,1,0]
	v_pk_fma_f32 v[104:105], v[114:115], v[106:107], v[104:105] op_sel:[0,1,0]
	v_add_f32_dpp v106, v138, v138 quad_perm:[1,0,3,2] row_mask:0xf bank_mask:0xf bound_ctrl:1
	v_add_f32_dpp v107, v139, v139 quad_perm:[1,0,3,2] row_mask:0xf bank_mask:0xf bound_ctrl:1
	v_pk_fma_f32 v[140:141], v[140:141], v[136:137], v[142:143]
	v_add_f32_dpp v106, v106, v106 quad_perm:[2,3,0,1] row_mask:0xf bank_mask:0xf bound_ctrl:1
	v_add_f32_dpp v107, v107, v107 quad_perm:[2,3,0,1] row_mask:0xf bank_mask:0xf bound_ctrl:1
	v_add_f32_e32 v172, v140, v141
	v_add_f32_dpp v106, v106, v106 row_ror:4 row_mask:0xf bank_mask:0xf bound_ctrl:1
	v_add_f32_dpp v107, v107, v107 row_ror:4 row_mask:0xf bank_mask:0xf bound_ctrl:1
	s_nop 0
	v_add_f32_dpp v106, v106, v106 row_ror:8 row_mask:0xf bank_mask:0xf bound_ctrl:1
	v_add_f32_dpp v110, v107, v107 row_ror:8 row_mask:0xf bank_mask:0xf bound_ctrl:1
	v_pk_fma_f32 v[162:163], v[94:95], v[106:107], v[118:119] op_sel_hi:[1,0,1] neg_lo:[1,0,0] neg_hi:[1,0,0]
	v_pk_fma_f32 v[160:161], v[94:95], v[110:111], v[104:105] op_sel_hi:[1,0,1] neg_lo:[1,0,0] neg_hi:[1,0,0]
	v_pk_fma_f32 v[166:167], v[92:93], v[106:107], v[116:117] op_sel_hi:[1,0,1] neg_lo:[1,0,0] neg_hi:[1,0,0]
	v_pk_fma_f32 v[164:165], v[92:93], v[110:111], v[108:109] op_sel_hi:[1,0,1] neg_lo:[1,0,0] neg_hi:[1,0,0]
	s_waitcnt lgkmcnt(11)
	v_pk_mul_f32 v[92:93], v[98:99], v[162:163]
	v_pk_mul_f32 v[94:95], v[98:99], v[160:161]
	v_pk_fma_f32 v[92:93], v[96:97], v[166:167], v[92:93]
	v_pk_fma_f32 v[94:95], v[96:97], v[164:165], v[94:95]
	v_add_f32_e32 v173, v92, v93
	v_add_f32_e32 v174, v94, v95
	ds_read2_b64 v[104:107], v168 offset0:96 offset1:112
	ds_read_b128 v[144:147], v244 offset:5632
	ds_read_b128 v[108:111], v244 offset:5888
	ds_read_b128 v[156:159], v244 offset:13824
	ds_read_b128 v[116:119], v244 offset:14080
	ds_read_b128 v[136:139], v244 offset:22016
	ds_read_b128 v[92:95], v244 offset:22272
	ds_read_b128 v[148:151], v244 offset:30208
	ds_read_b128 v[112:115], v244 offset:30464
	ds_read_b128 v[140:143], v244 offset:38400
	ds_read_b128 v[96:99], v244 offset:38656
	s_waitcnt lgkmcnt(14)
	v_pk_mul_f32 v[170:171], v[154:155], v[162:163]
	v_pk_mul_f32 v[154:155], v[154:155], v[160:161]
	v_pk_fma_f32 v[170:171], v[152:153], v[166:167], v[170:171]
	v_pk_fma_f32 v[152:153], v[152:153], v[164:165], v[154:155]
	v_add_f32_e32 v154, v170, v171
	v_cndmask_b32_e64 v170, v169, v172, s[6:7]
	v_cndmask_b32_e64 v171, v173, v174, s[6:7]
	v_cndmask_b32_e64 v169, v172, v169, s[6:7]
	v_cndmask_b32_e64 v172, v174, v173, s[6:7]
	v_add_f32_e32 v152, v152, v153
	v_add_f32_dpp v169, v170, v169 quad_perm:[1,0,3,2] row_mask:0xf bank_mask:0xf bound_ctrl:1
	v_add_f32_dpp v170, v171, v172 quad_perm:[1,0,3,2] row_mask:0xf bank_mask:0xf bound_ctrl:1
	v_add_f32_dpp v153, v154, v154 quad_perm:[1,0,3,2] row_mask:0xf bank_mask:0xf bound_ctrl:1
	v_add_f32_dpp v152, v152, v152 quad_perm:[1,0,3,2] row_mask:0xf bank_mask:0xf bound_ctrl:1
	v_cndmask_b32_e64 v171, v169, v170, s[8:9]
	v_cndmask_b32_e64 v169, v170, v169, s[8:9]
	v_add_f32_dpp v153, v153, v153 quad_perm:[2,3,0,1] row_mask:0xf bank_mask:0xf bound_ctrl:1
	v_add_f32_dpp v154, v152, v152 quad_perm:[2,3,0,1] row_mask:0xf bank_mask:0xf bound_ctrl:1
	v_add_f32_dpp v169, v171, v169 quad_perm:[2,3,0,1] row_mask:0xf bank_mask:0xf bound_ctrl:1
	v_add_f32_dpp v152, v153, v153 row_ror:4 row_mask:0xf bank_mask:0xf bound_ctrl:1
	v_add_f32_dpp v153, v154, v154 row_ror:4 row_mask:0xf bank_mask:0xf bound_ctrl:1
	v_mov_b32_e32 v154, 0
	v_mov_b32_e32 v155, 0
	v_add_f32_dpp v169, v169, v169 row_ror:4 row_mask:0xf bank_mask:0xf bound_ctrl:1
	v_mov_b32_e32 v170, 0
	v_mov_b32_dpp v154, v152 row_ror:8 row_mask:0xf bank_mask:0xf
	v_mov_b32_dpp v155, v153 row_ror:8 row_mask:0xf bank_mask:0xf
	v_mov_b32_dpp v170, v169 row_ror:8 row_mask:0xf bank_mask:0xf
	s_and_saveexec_b64 s[78:79], s[10:11]
	v_add_f32_e32 v169, v169, v170
	ds_write_b32 v245, v169 offset:2304
	s_or_b64 exec, exec, s[78:79]
	v_pk_mul_f32 v[166:167], v[128:129], v[166:167]
	v_pk_mul_f32 v[162:163], v[130:131], v[162:163]
	v_pk_mul_f32 v[128:129], v[128:129], v[164:165]
	v_pk_mul_f32 v[130:131], v[130:131], v[160:161]
	v_pk_fma_f32 v[166:167], v[132:133], v[80:81], v[166:167] op_sel_hi:[1,0,1]
	v_pk_fma_f32 v[162:163], v[134:135], v[80:81], v[162:163] op_sel_hi:[1,0,1]
	v_pk_fma_f32 v[128:129], v[132:133], v[80:81], v[128:129] op_sel:[0,1,0]
	v_pk_fma_f32 v[80:81], v[134:135], v[80:81], v[130:131] op_sel:[0,1,0]
	v_add_f32_e32 v130, v152, v154
	v_add_f32_e32 v132, v153, v155
	v_pk_fma_f32 v[134:135], v[120:121], v[130:131], v[166:167] op_sel_hi:[1,0,1] neg_lo:[1,0,0] neg_hi:[1,0,0]
	v_pk_fma_f32 v[130:131], v[122:123], v[130:131], v[162:163] op_sel_hi:[1,0,1] neg_lo:[1,0,0] neg_hi:[1,0,0]
	v_pk_fma_f32 v[80:81], v[122:123], v[132:133], v[80:81] op_sel_hi:[1,0,1] neg_lo:[1,0,0] neg_hi:[1,0,0]
	s_waitcnt lgkmcnt(12)
	v_pk_mul_f32 v[122:123], v[126:127], v[130:131]
	v_pk_fma_f32 v[120:121], v[120:121], v[132:133], v[128:129] op_sel_hi:[1,0,1] neg_lo:[1,0,0] neg_hi:[1,0,0]
	v_pk_fma_f32 v[122:123], v[124:125], v[134:135], v[122:123]
	v_pk_mul_f32 v[126:127], v[126:127], v[80:81]
	s_nop 0
	v_pk_fma_f32 v[124:125], v[124:125], v[120:121], v[126:127]
	v_add_f32_e32 v126, v122, v123
	v_pk_mul_f32 v[122:123], v[102:103], v[130:131]
	v_pk_mul_f32 v[102:103], v[102:103], v[80:81]
	v_pk_fma_f32 v[122:123], v[100:101], v[134:135], v[122:123]
	v_pk_fma_f32 v[100:101], v[100:101], v[120:121], v[102:103]
	v_add_f32_e32 v122, v122, v123
	v_add_f32_e32 v123, v100, v101
	v_pk_mul_f32 v[80:81], v[86:87], v[80:81]
	v_pk_mul_f32 v[102:103], v[86:87], v[130:131]
	v_pk_fma_f32 v[86:87], v[90:91], v[82:83], v[80:81] op_sel:[0,1,0]
	v_add_f32_dpp v80, v122, v122 quad_perm:[1,0,3,2] row_mask:0xf bank_mask:0xf bound_ctrl:1
	v_add_f32_dpp v81, v123, v123 quad_perm:[1,0,3,2] row_mask:0xf bank_mask:0xf bound_ctrl:1
	v_pk_mul_f32 v[100:101], v[84:85], v[134:135]
	v_add_f32_dpp v80, v80, v80 quad_perm:[2,3,0,1] row_mask:0xf bank_mask:0xf bound_ctrl:1
	v_add_f32_dpp v81, v81, v81 quad_perm:[2,3,0,1] row_mask:0xf bank_mask:0xf bound_ctrl:1
	v_pk_mul_f32 v[84:85], v[84:85], v[120:121]
	v_add_f32_dpp v80, v80, v80 row_ror:4 row_mask:0xf bank_mask:0xf bound_ctrl:1
	v_add_f32_dpp v81, v81, v81 row_ror:4 row_mask:0xf bank_mask:0xf bound_ctrl:1
	v_pk_fma_f32 v[100:101], v[88:89], v[82:83], v[100:101] op_sel_hi:[1,0,1]
	v_pk_fma_f32 v[102:103], v[90:91], v[82:83], v[102:103] op_sel_hi:[1,0,1]
	v_pk_fma_f32 v[88:89], v[88:89], v[82:83], v[84:85] op_sel:[0,1,0]
	v_add_f32_dpp v80, v80, v80 row_ror:8 row_mask:0xf bank_mask:0xf bound_ctrl:1
	v_add_f32_dpp v90, v81, v81 row_ror:8 row_mask:0xf bank_mask:0xf bound_ctrl:1
	v_pk_fma_f32 v[84:85], v[72:73], v[80:81], v[100:101] op_sel_hi:[1,0,1] neg_lo:[1,0,0] neg_hi:[1,0,0]
	v_pk_fma_f32 v[80:81], v[74:75], v[80:81], v[102:103] op_sel_hi:[1,0,1] neg_lo:[1,0,0] neg_hi:[1,0,0]
	v_pk_fma_f32 v[82:83], v[72:73], v[90:91], v[88:89] op_sel_hi:[1,0,1] neg_lo:[1,0,0] neg_hi:[1,0,0]
	v_pk_fma_f32 v[72:73], v[74:75], v[90:91], v[86:87] op_sel_hi:[1,0,1] neg_lo:[1,0,0] neg_hi:[1,0,0]
	s_waitcnt lgkmcnt(11)
	v_pk_mul_f32 v[74:75], v[78:79], v[80:81]
	v_pk_mul_f32 v[78:79], v[78:79], v[72:73]
	v_pk_fma_f32 v[74:75], v[76:77], v[84:85], v[74:75]
	v_pk_fma_f32 v[76:77], v[76:77], v[82:83], v[78:79]
	v_add_f32_e32 v78, v74, v75
	v_add_f32_e32 v79, v76, v77
	v_add_f32_e32 v124, v124, v125
	s_waitcnt lgkmcnt(7)
	v_pk_mul_f32 v[74:75], v[158:159], v[80:81]
	v_pk_mul_f32 v[76:77], v[158:159], v[72:73]
	v_pk_fma_f32 v[74:75], v[156:157], v[84:85], v[74:75]
	v_pk_fma_f32 v[76:77], v[156:157], v[82:83], v[76:77]
	v_cndmask_b32_e64 v86, v126, v124, s[6:7]
	v_cndmask_b32_e64 v87, v78, v79, s[6:7]
	v_cndmask_b32_e64 v88, v124, v126, s[6:7]
	v_cndmask_b32_e64 v78, v79, v78, s[6:7]
	v_add_f32_e32 v74, v74, v75
	v_add_f32_e32 v75, v76, v77
	v_add_f32_dpp v79, v86, v88 quad_perm:[1,0,3,2] row_mask:0xf bank_mask:0xf bound_ctrl:1
	v_add_f32_dpp v78, v87, v78 quad_perm:[1,0,3,2] row_mask:0xf bank_mask:0xf bound_ctrl:1
	v_add_f32_dpp v74, v74, v74 quad_perm:[1,0,3,2] row_mask:0xf bank_mask:0xf bound_ctrl:1
	v_add_f32_dpp v75, v75, v75 quad_perm:[1,0,3,2] row_mask:0xf bank_mask:0xf bound_ctrl:1
	v_cndmask_b32_e64 v86, v79, v78, s[8:9]
	v_cndmask_b32_e64 v78, v78, v79, s[8:9]
	v_add_f32_dpp v74, v74, v74 quad_perm:[2,3,0,1] row_mask:0xf bank_mask:0xf bound_ctrl:1
	v_add_f32_dpp v75, v75, v75 quad_perm:[2,3,0,1] row_mask:0xf bank_mask:0xf bound_ctrl:1
	v_add_f32_dpp v78, v86, v78 quad_perm:[2,3,0,1] row_mask:0xf bank_mask:0xf bound_ctrl:1
	v_add_f32_dpp v74, v74, v74 row_ror:4 row_mask:0xf bank_mask:0xf bound_ctrl:1
	v_add_f32_dpp v75, v75, v75 row_ror:4 row_mask:0xf bank_mask:0xf bound_ctrl:1
	v_mov_b32_e32 v76, 0
	v_mov_b32_e32 v77, 0
	v_add_f32_dpp v78, v78, v78 row_ror:4 row_mask:0xf bank_mask:0xf bound_ctrl:1
	v_mov_b32_e32 v79, 0
	v_mov_b32_dpp v76, v74 row_ror:8 row_mask:0xf bank_mask:0xf
	v_mov_b32_dpp v77, v75 row_ror:8 row_mask:0xf bank_mask:0xf
	v_mov_b32_dpp v79, v78 row_ror:8 row_mask:0xf bank_mask:0xf
	s_and_saveexec_b64 s[78:79], s[10:11]
	v_add_f32_e32 v78, v78, v79
	ds_write_b32 v245, v78 offset:2560
	s_or_b64 exec, exec, s[78:79]
	v_pk_mul_f32 v[78:79], v[144:145], v[84:85]
	v_pk_mul_f32 v[80:81], v[146:147], v[80:81]
	v_pk_mul_f32 v[72:73], v[146:147], v[72:73]
	s_waitcnt lgkmcnt(3)
	v_pk_fma_f32 v[78:79], v[148:149], v[104:105], v[78:79] op_sel_hi:[1,0,1]
	v_pk_fma_f32 v[80:81], v[150:151], v[104:105], v[80:81] op_sel_hi:[1,0,1]
	v_pk_mul_f32 v[82:83], v[144:145], v[82:83]
	v_pk_fma_f32 v[72:73], v[150:151], v[104:105], v[72:73] op_sel:[0,1,0]
	v_add_f32_e32 v74, v74, v76
	v_add_f32_e32 v76, v75, v77
	v_pk_fma_f32 v[82:83], v[148:149], v[104:105], v[82:83] op_sel:[0,1,0]
	v_pk_fma_f32 v[78:79], v[136:137], v[74:75], v[78:79] op_sel_hi:[1,0,1] neg_lo:[1,0,0] neg_hi:[1,0,0]
	v_pk_fma_f32 v[74:75], v[138:139], v[74:75], v[80:81] op_sel_hi:[1,0,1] neg_lo:[1,0,0] neg_hi:[1,0,0]
	v_pk_fma_f32 v[72:73], v[138:139], v[76:77], v[72:73] op_sel_hi:[1,0,1] neg_lo:[1,0,0] neg_hi:[1,0,0]
	v_pk_fma_f32 v[80:81], v[136:137], v[76:77], v[82:83] op_sel_hi:[1,0,1] neg_lo:[1,0,0] neg_hi:[1,0,0]
	s_waitcnt lgkmcnt(1)
	v_pk_mul_f32 v[76:77], v[142:143], v[74:75]
	v_pk_mul_f32 v[82:83], v[142:143], v[72:73]
	v_pk_fma_f32 v[76:77], v[140:141], v[78:79], v[76:77]
	v_pk_fma_f32 v[82:83], v[140:141], v[80:81], v[82:83]
	v_add_f32_e32 v84, v76, v77
	v_add_f32_e32 v85, v82, v83
	v_pk_mul_f32 v[76:77], v[118:119], v[74:75]
	v_pk_mul_f32 v[82:83], v[118:119], v[72:73]
	v_pk_fma_f32 v[76:77], v[116:117], v[78:79], v[76:77]
	v_pk_fma_f32 v[82:83], v[116:117], v[80:81], v[82:83]
	v_add_f32_e32 v86, v76, v77
	v_add_f32_e32 v82, v82, v83
	v_pk_mul_f32 v[76:77], v[108:109], v[78:79]
	v_pk_mul_f32 v[78:79], v[108:109], v[80:81]
	v_add_f32_dpp v80, v86, v86 quad_perm:[1,0,3,2] row_mask:0xf bank_mask:0xf bound_ctrl:1
	v_add_f32_dpp v81, v82, v82 quad_perm:[1,0,3,2] row_mask:0xf bank_mask:0xf bound_ctrl:1
	v_pk_mul_f32 v[74:75], v[110:111], v[74:75]
	v_add_f32_dpp v80, v80, v80 quad_perm:[2,3,0,1] row_mask:0xf bank_mask:0xf bound_ctrl:1
	v_add_f32_dpp v81, v81, v81 quad_perm:[2,3,0,1] row_mask:0xf bank_mask:0xf bound_ctrl:1
	v_pk_mul_f32 v[72:73], v[110:111], v[72:73]
	v_add_f32_dpp v80, v80, v80 row_ror:4 row_mask:0xf bank_mask:0xf bound_ctrl:1
	v_add_f32_dpp v81, v81, v81 row_ror:4 row_mask:0xf bank_mask:0xf bound_ctrl:1
	v_pk_fma_f32 v[74:75], v[114:115], v[106:107], v[74:75] op_sel_hi:[1,0,1]
	v_pk_fma_f32 v[72:73], v[114:115], v[106:107], v[72:73] op_sel:[0,1,0]
	v_add_f32_dpp v80, v80, v80 row_ror:8 row_mask:0xf bank_mask:0xf bound_ctrl:1
	v_add_f32_dpp v82, v81, v81 row_ror:8 row_mask:0xf bank_mask:0xf bound_ctrl:1
	v_pk_fma_f32 v[76:77], v[112:113], v[106:107], v[76:77] op_sel_hi:[1,0,1]
	v_pk_fma_f32 v[78:79], v[112:113], v[106:107], v[78:79] op_sel:[0,1,0]
	v_pk_fma_f32 v[90:91], v[94:95], v[80:81], v[74:75] op_sel_hi:[1,0,1] neg_lo:[1,0,0] neg_hi:[1,0,0]
	v_pk_fma_f32 v[94:95], v[94:95], v[82:83], v[72:73] op_sel_hi:[1,0,1] neg_lo:[1,0,0] neg_hi:[1,0,0]
	v_pk_fma_f32 v[88:89], v[92:93], v[80:81], v[76:77] op_sel_hi:[1,0,1] neg_lo:[1,0,0] neg_hi:[1,0,0]
	v_pk_fma_f32 v[92:93], v[92:93], v[82:83], v[78:79] op_sel_hi:[1,0,1] neg_lo:[1,0,0] neg_hi:[1,0,0]
	s_waitcnt lgkmcnt(0)
	v_pk_mul_f32 v[72:73], v[98:99], v[90:91]
	v_pk_mul_f32 v[74:75], v[98:99], v[94:95]
	v_pk_fma_f32 v[72:73], v[96:97], v[88:89], v[72:73]
	v_pk_fma_f32 v[74:75], v[96:97], v[92:93], v[74:75]
	v_add_f32_e32 v72, v72, v73
	v_add_f32_e32 v73, v74, v75
	v_cndmask_b32_e64 v74, v84, v85, s[6:7]
	v_cndmask_b32_e64 v75, v72, v73, s[6:7]
	v_cndmask_b32_e64 v76, v85, v84, s[6:7]
	v_cndmask_b32_e64 v72, v73, v72, s[6:7]
	s_nop 0
	v_add_f32_dpp v73, v74, v76 quad_perm:[1,0,3,2] row_mask:0xf bank_mask:0xf bound_ctrl:1
	v_add_f32_dpp v72, v75, v72 quad_perm:[1,0,3,2] row_mask:0xf bank_mask:0xf bound_ctrl:1
	v_cndmask_b32_e64 v74, v73, v72, s[8:9]
	v_cndmask_b32_e64 v72, v72, v73, s[8:9]
	v_mov_b32_e32 v73, 0
	s_nop 0
	v_add_f32_dpp v72, v74, v72 quad_perm:[2,3,0,1] row_mask:0xf bank_mask:0xf bound_ctrl:1
	s_nop 1
	v_add_f32_dpp v72, v72, v72 row_ror:4 row_mask:0xf bank_mask:0xf bound_ctrl:1
	s_nop 1
	v_mov_b32_dpp v73, v72 row_ror:8 row_mask:0xf bank_mask:0xf
	s_and_saveexec_b64 s[78:79], s[10:11]
	v_add3_u32 v74, v176, v239, v197
	v_add_f32_e32 v72, v72, v73
	ds_write_b32 v74, v72 offset:2816
	s_or_b64 exec, exec, s[78:79]
	s_setprio 0
	s_ashr_i32 s28, s24, 5
	s_add_i32 s29, s24, 0xffffff00
	s_not_b32 s28, s28
	s_lshr_b32 s29, s29, 5
	s_cmpk_lt_i32 s24, 0x100
	s_cselect_b32 s28, s28, s29
	s_ashr_i32 s29, s28, 31
	s_lshl_b32 s24, s24, 5
	s_lshl_b64 s[28:29], s[28:29], 10
	s_and_b32 s24, s24, 0x3e0
	s_or_b32 s24, s28, s24
	v_mov_b32_e32 v73, s29
	v_or_b32_e32 v72, s24, v192
	v_lshlrev_b64 v[72:73], 8, v[72:73]
	v_lshl_add_u64 v[72:73], v[198:199], 0, v[72:73]
	global_store_dwordx4 v[72:73], v[88:91], off
	global_store_dwordx4 v[72:73], v[92:95], off offset:256
	s_mul_i32 s24, s94, 3
	s_add_i32 s24, s70, s24
	s_cmpk_gt_i32 s24, 0x10ff
	s_cbranch_scc1 .LBB0_346
.LBB0_337:
	s_setprio 0
	ds_read2_b64 v[72:75], v168 offset0:128 offset1:144
	ds_read_b128 v[76:79], v244 offset:39168
	ds_read_b128 v[80:83], v244 offset:38912
	ds_read_b128 v[88:91], v244 offset:30976
	ds_read_b128 v[112:115], v244 offset:30720
	ds_read_b128 v[116:119], v244 offset:22784
	ds_read_b128 v[120:123], v244 offset:22528
	ds_read_b128 v[124:127], v244 offset:14592
	ds_read_b128 v[144:147], v244 offset:14336
	ds_read_b128 v[148:151], v244 offset:6400
	ds_read_b128 v[152:155], v244 offset:6144
	ds_read2_b64 v[96:99], v168 offset0:160 offset1:176
	ds_read_b128 v[136:139], v244 offset:6656
	ds_read_b128 v[100:103], v244 offset:6912
	ds_read_b128 v[156:159], v244 offset:14848
	ds_read_b128 v[108:111], v244 offset:15104
	ds_read_b128 v[128:131], v244 offset:23040
	ds_read_b128 v[84:87], v244 offset:23296
	ds_read_b128 v[140:143], v244 offset:31232
	ds_read_b128 v[104:107], v244 offset:31488
	ds_read_b128 v[132:135], v244 offset:39424
	ds_read_b128 v[92:95], v244 offset:39680
	s_waitcnt lgkmcnt(13)
	v_pk_mul_f32 v[160:161], v[66:67], v[146:147]
	v_pk_mul_f32 v[146:147], v[70:71], v[146:147]
	v_pk_fma_f32 v[160:161], v[64:65], v[144:145], v[160:161]
	v_pk_fma_f32 v[144:145], v[68:69], v[144:145], v[146:147]
	v_add_f32_e32 v146, v160, v161
	v_add_f32_e32 v144, v144, v145
	s_waitcnt lgkmcnt(11)
	v_pk_mul_f32 v[68:69], v[68:69], v[152:153]
	v_add_f32_dpp v145, v146, v146 quad_perm:[1,0,3,2] row_mask:0xf bank_mask:0xf bound_ctrl:1
	v_add_f32_dpp v144, v144, v144 quad_perm:[1,0,3,2] row_mask:0xf bank_mask:0xf bound_ctrl:1
	v_pk_mul_f32 v[64:65], v[64:65], v[152:153]
	v_add_f32_dpp v145, v145, v145 quad_perm:[2,3,0,1] row_mask:0xf bank_mask:0xf bound_ctrl:1
	v_add_f32_dpp v144, v144, v144 quad_perm:[2,3,0,1] row_mask:0xf bank_mask:0xf bound_ctrl:1
	v_pk_mul_f32 v[66:67], v[66:67], v[154:155]
	v_add_f32_dpp v146, v145, v145 row_ror:4 row_mask:0xf bank_mask:0xf bound_ctrl:1
	v_add_f32_dpp v144, v144, v144 row_ror:4 row_mask:0xf bank_mask:0xf bound_ctrl:1
	v_pk_fma_f32 v[68:69], v[72:73], v[112:113], v[68:69] op_sel:[1,0,0]
	v_pk_mul_f32 v[70:71], v[70:71], v[154:155]
	v_pk_fma_f32 v[64:65], v[72:73], v[112:113], v[64:65] op_sel_hi:[0,1,1]
	v_add_f32_dpp v112, v146, v146 row_ror:8 row_mask:0xf bank_mask:0xf bound_ctrl:1
	v_pk_fma_f32 v[66:67], v[72:73], v[114:115], v[66:67] op_sel_hi:[0,1,1]
	v_add_f32_dpp v144, v144, v144 row_ror:8 row_mask:0xf bank_mask:0xf bound_ctrl:1
	v_pk_fma_f32 v[70:71], v[72:73], v[114:115], v[70:71] op_sel:[1,0,0]
	v_pk_fma_f32 v[66:67], v[122:123], v[112:113], v[66:67] op_sel_hi:[1,0,1] neg_lo:[1,0,0] neg_hi:[1,0,0]
	v_pk_fma_f32 v[70:71], v[122:123], v[144:145], v[70:71] op_sel_hi:[1,0,1] neg_lo:[1,0,0] neg_hi:[1,0,0]
	v_pk_fma_f32 v[64:65], v[120:121], v[112:113], v[64:65] op_sel_hi:[1,0,1] neg_lo:[1,0,0] neg_hi:[1,0,0]
	v_pk_mul_f32 v[72:73], v[82:83], v[66:67]
	v_pk_fma_f32 v[68:69], v[120:121], v[144:145], v[68:69] op_sel_hi:[1,0,1] neg_lo:[1,0,0] neg_hi:[1,0,0]
	v_pk_mul_f32 v[144:145], v[82:83], v[70:71]
	v_pk_fma_f32 v[72:73], v[80:81], v[64:65], v[72:73]
	v_pk_fma_f32 v[144:145], v[80:81], v[68:69], v[144:145]
	v_add_f32_e32 v163, v72, v73
	v_pk_mul_f32 v[72:73], v[126:127], v[66:67]
	v_pk_mul_f32 v[80:81], v[126:127], v[70:71]
	v_pk_fma_f32 v[72:73], v[124:125], v[64:65], v[72:73]
	v_pk_fma_f32 v[80:81], v[124:125], v[68:69], v[80:81]
	v_add_f32_e32 v72, v72, v73
	v_add_f32_e32 v73, v80, v81
	v_pk_mul_f32 v[64:65], v[148:149], v[64:65]
	v_add_f32_dpp v72, v72, v72 quad_perm:[1,0,3,2] row_mask:0xf bank_mask:0xf bound_ctrl:1
	v_add_f32_dpp v73, v73, v73 quad_perm:[1,0,3,2] row_mask:0xf bank_mask:0xf bound_ctrl:1
	v_pk_mul_f32 v[66:67], v[150:151], v[66:67]
	v_add_f32_dpp v72, v72, v72 quad_perm:[2,3,0,1] row_mask:0xf bank_mask:0xf bound_ctrl:1
	v_add_f32_dpp v73, v73, v73 quad_perm:[2,3,0,1] row_mask:0xf bank_mask:0xf bound_ctrl:1
	v_pk_mul_f32 v[68:69], v[148:149], v[68:69]
	v_pk_mul_f32 v[70:71], v[150:151], v[70:71]
	v_add_f32_dpp v72, v72, v72 row_ror:4 row_mask:0xf bank_mask:0xf bound_ctrl:1
	v_add_f32_dpp v73, v73, v73 row_ror:4 row_mask:0xf bank_mask:0xf bound_ctrl:1
	v_pk_fma_f32 v[64:65], v[74:75], v[88:89], v[64:65] op_sel_hi:[0,1,1]
	v_pk_fma_f32 v[66:67], v[74:75], v[90:91], v[66:67] op_sel_hi:[0,1,1]
	v_pk_fma_f32 v[68:69], v[74:75], v[88:89], v[68:69] op_sel:[1,0,0]
	v_pk_fma_f32 v[70:71], v[74:75], v[90:91], v[70:71] op_sel:[1,0,0]
	v_add_f32_dpp v72, v72, v72 row_ror:8 row_mask:0xf bank_mask:0xf bound_ctrl:1
	v_add_f32_dpp v74, v73, v73 row_ror:8 row_mask:0xf bank_mask:0xf bound_ctrl:1
	v_pk_fma_f32 v[150:151], v[118:119], v[72:73], v[66:67] op_sel_hi:[1,0,1] neg_lo:[1,0,0] neg_hi:[1,0,0]
	v_pk_fma_f32 v[148:149], v[118:119], v[74:75], v[70:71] op_sel_hi:[1,0,1] neg_lo:[1,0,0] neg_hi:[1,0,0]
	v_pk_fma_f32 v[154:155], v[116:117], v[72:73], v[64:65] op_sel_hi:[1,0,1] neg_lo:[1,0,0] neg_hi:[1,0,0]
	v_pk_fma_f32 v[152:153], v[116:117], v[74:75], v[68:69] op_sel_hi:[1,0,1] neg_lo:[1,0,0] neg_hi:[1,0,0]
	v_pk_mul_f32 v[64:65], v[78:79], v[150:151]
	v_pk_mul_f32 v[66:67], v[78:79], v[148:149]
	v_pk_fma_f32 v[64:65], v[76:77], v[154:155], v[64:65]
	v_pk_fma_f32 v[66:67], v[76:77], v[152:153], v[66:67]
	v_add_f32_e32 v162, v144, v145
	v_add_f32_e32 v164, v64, v65
	v_add_f32_e32 v165, v66, v67
	ds_read2_b64 v[72:75], v168 offset0:192 offset1:208
	ds_read_b128 v[120:123], v244 offset:7168
	ds_read_b128 v[76:79], v244 offset:7424
	ds_read_b128 v[144:147], v244 offset:15360
	ds_read_b128 v[88:91], v244 offset:15616
	ds_read_b128 v[112:115], v244 offset:23552
	ds_read_b128 v[64:67], v244 offset:23808
	ds_read_b128 v[124:127], v244 offset:31744
	ds_read_b128 v[80:83], v244 offset:32000
	ds_read_b128 v[116:119], v244 offset:39936
	ds_read_b128 v[68:71], v244 offset:40192
	s_waitcnt lgkmcnt(14)
	v_pk_mul_f32 v[160:161], v[158:159], v[150:151]
	v_pk_mul_f32 v[158:159], v[158:159], v[148:149]
	v_pk_fma_f32 v[160:161], v[156:157], v[154:155], v[160:161]
	v_pk_fma_f32 v[156:157], v[156:157], v[152:153], v[158:159]
	v_add_f32_e32 v158, v160, v161
	v_cndmask_b32_e64 v160, v163, v162, s[6:7]
	v_cndmask_b32_e64 v161, v164, v165, s[6:7]
	v_cndmask_b32_e64 v162, v162, v163, s[6:7]
	v_cndmask_b32_e64 v163, v165, v164, s[6:7]
	v_add_f32_e32 v156, v156, v157
	v_add_f32_dpp v160, v160, v162 quad_perm:[1,0,3,2] row_mask:0xf bank_mask:0xf bound_ctrl:1
	v_add_f32_dpp v161, v161, v163 quad_perm:[1,0,3,2] row_mask:0xf bank_mask:0xf bound_ctrl:1
	v_add_f32_dpp v157, v158, v158 quad_perm:[1,0,3,2] row_mask:0xf bank_mask:0xf bound_ctrl:1
	v_add_f32_dpp v156, v156, v156 quad_perm:[1,0,3,2] row_mask:0xf bank_mask:0xf bound_ctrl:1
	v_cndmask_b32_e64 v162, v160, v161, s[8:9]
	v_cndmask_b32_e64 v160, v161, v160, s[8:9]
	v_add_f32_dpp v157, v157, v157 quad_perm:[2,3,0,1] row_mask:0xf bank_mask:0xf bound_ctrl:1
	v_add_f32_dpp v158, v156, v156 quad_perm:[2,3,0,1] row_mask:0xf bank_mask:0xf bound_ctrl:1
	v_add_f32_dpp v160, v162, v160 quad_perm:[2,3,0,1] row_mask:0xf bank_mask:0xf bound_ctrl:1
	v_add_f32_dpp v156, v157, v157 row_ror:4 row_mask:0xf bank_mask:0xf bound_ctrl:1
	v_add_f32_dpp v157, v158, v158 row_ror:4 row_mask:0xf bank_mask:0xf bound_ctrl:1
	v_mov_b32_e32 v158, v177
	v_mov_b32_e32 v159, v177
	v_add_f32_dpp v160, v160, v160 row_ror:4 row_mask:0xf bank_mask:0xf bound_ctrl:1
	v_mov_b32_e32 v161, v177
	v_mov_b32_dpp v158, v156 row_ror:8 row_mask:0xf bank_mask:0xf
	v_mov_b32_dpp v159, v157 row_ror:8 row_mask:0xf bank_mask:0xf
	v_mov_b32_dpp v161, v160 row_ror:8 row_mask:0xf bank_mask:0xf
	s_and_saveexec_b64 s[78:79], s[10:11]
	v_add_f32_e32 v160, v160, v161
	ds_write_b32 v245, v160 offset:3072
	s_or_b64 exec, exec, s[78:79]
	v_pk_mul_f32 v[154:155], v[136:137], v[154:155]
	v_pk_mul_f32 v[150:151], v[138:139], v[150:151]
	v_pk_mul_f32 v[136:137], v[136:137], v[152:153]
	v_pk_mul_f32 v[138:139], v[138:139], v[148:149]
	v_pk_fma_f32 v[154:155], v[140:141], v[96:97], v[154:155] op_sel_hi:[1,0,1]
	v_pk_fma_f32 v[150:151], v[142:143], v[96:97], v[150:151] op_sel_hi:[1,0,1]
	v_pk_fma_f32 v[136:137], v[140:141], v[96:97], v[136:137] op_sel:[0,1,0]
	v_pk_fma_f32 v[96:97], v[142:143], v[96:97], v[138:139] op_sel:[0,1,0]
	v_add_f32_e32 v138, v156, v158
	v_add_f32_e32 v140, v157, v159
	v_pk_fma_f32 v[142:143], v[128:129], v[138:139], v[154:155] op_sel_hi:[1,0,1] neg_lo:[1,0,0] neg_hi:[1,0,0]
	v_pk_fma_f32 v[138:139], v[130:131], v[138:139], v[150:151] op_sel_hi:[1,0,1] neg_lo:[1,0,0] neg_hi:[1,0,0]
	v_pk_fma_f32 v[96:97], v[130:131], v[140:141], v[96:97] op_sel_hi:[1,0,1] neg_lo:[1,0,0] neg_hi:[1,0,0]
	s_waitcnt lgkmcnt(12)
	v_pk_mul_f32 v[130:131], v[134:135], v[138:139]
	v_pk_fma_f32 v[128:129], v[128:129], v[140:141], v[136:137] op_sel_hi:[1,0,1] neg_lo:[1,0,0] neg_hi:[1,0,0]
	v_pk_fma_f32 v[130:131], v[132:133], v[142:143], v[130:131]
	v_pk_mul_f32 v[134:135], v[134:135], v[96:97]
	v_add_f32_e32 v162, v130, v131
	v_pk_mul_f32 v[130:131], v[110:111], v[138:139]
	v_pk_mul_f32 v[110:111], v[110:111], v[96:97]
	v_pk_fma_f32 v[130:131], v[108:109], v[142:143], v[130:131]
	v_pk_fma_f32 v[108:109], v[108:109], v[128:129], v[110:111]
	v_add_f32_e32 v130, v130, v131
	v_add_f32_e32 v131, v108, v109
	v_pk_mul_f32 v[108:109], v[100:101], v[142:143]
	v_pk_mul_f32 v[110:111], v[102:103], v[138:139]
	v_pk_mul_f32 v[100:101], v[100:101], v[128:129]
	v_pk_mul_f32 v[96:97], v[102:103], v[96:97]
	v_pk_fma_f32 v[108:109], v[104:105], v[98:99], v[108:109] op_sel_hi:[1,0,1]
	v_pk_fma_f32 v[110:111], v[106:107], v[98:99], v[110:111] op_sel_hi:[1,0,1]
	v_pk_fma_f32 v[100:101], v[104:105], v[98:99], v[100:101] op_sel:[0,1,0]
	v_pk_fma_f32 v[96:97], v[106:107], v[98:99], v[96:97] op_sel:[0,1,0]
	v_add_f32_dpp v98, v130, v130 quad_perm:[1,0,3,2] row_mask:0xf bank_mask:0xf bound_ctrl:1
	v_add_f32_dpp v99, v131, v131 quad_perm:[1,0,3,2] row_mask:0xf bank_mask:0xf bound_ctrl:1
	v_pk_fma_f32 v[132:133], v[132:133], v[128:129], v[134:135]
	v_add_f32_dpp v98, v98, v98 quad_perm:[2,3,0,1] row_mask:0xf bank_mask:0xf bound_ctrl:1
	v_add_f32_dpp v99, v99, v99 quad_perm:[2,3,0,1] row_mask:0xf bank_mask:0xf bound_ctrl:1
	v_add_f32_e32 v163, v132, v133
	v_add_f32_dpp v98, v98, v98 row_ror:4 row_mask:0xf bank_mask:0xf bound_ctrl:1
	v_add_f32_dpp v99, v99, v99 row_ror:4 row_mask:0xf bank_mask:0xf bound_ctrl:1
	s_nop 0
	v_add_f32_dpp v98, v98, v98 row_ror:8 row_mask:0xf bank_mask:0xf bound_ctrl:1
	v_add_f32_dpp v102, v99, v99 row_ror:8 row_mask:0xf bank_mask:0xf bound_ctrl:1
	v_pk_fma_f32 v[154:155], v[86:87], v[98:99], v[110:111] op_sel_hi:[1,0,1] neg_lo:[1,0,0] neg_hi:[1,0,0]
	v_pk_fma_f32 v[152:153], v[86:87], v[102:103], v[96:97] op_sel_hi:[1,0,1] neg_lo:[1,0,0] neg_hi:[1,0,0]
	v_pk_fma_f32 v[158:159], v[84:85], v[98:99], v[108:109] op_sel_hi:[1,0,1] neg_lo:[1,0,0] neg_hi:[1,0,0]
	v_pk_fma_f32 v[156:157], v[84:85], v[102:103], v[100:101] op_sel_hi:[1,0,1] neg_lo:[1,0,0] neg_hi:[1,0,0]
	s_waitcnt lgkmcnt(11)
	v_pk_mul_f32 v[84:85], v[94:95], v[154:155]
	v_pk_mul_f32 v[86:87], v[94:95], v[152:153]
	v_pk_fma_f32 v[84:85], v[92:93], v[158:159], v[84:85]
	v_pk_fma_f32 v[86:87], v[92:93], v[156:157], v[86:87]
	v_add_f32_e32 v164, v84, v85
	v_add_f32_e32 v165, v86, v87
	ds_read2_b64 v[92:95], v168 offset0:224 offset1:240
	ds_read_b128 v[136:139], v244 offset:7680
	ds_read_b128 v[100:103], v244 offset:7936
	ds_read_b128 v[148:151], v244 offset:15872
	ds_read_b128 v[108:111], v244 offset:16128
	ds_read_b128 v[128:131], v244 offset:24064
	ds_read_b128 v[84:87], v244 offset:24320
	ds_read_b128 v[140:143], v244 offset:32256
	ds_read_b128 v[104:107], v244 offset:32512
	ds_read_b128 v[132:135], v244 offset:40448
	ds_read_b128 v[96:99], v244 offset:40704
	s_waitcnt lgkmcnt(14)
	v_pk_mul_f32 v[160:161], v[146:147], v[154:155]
	v_pk_mul_f32 v[146:147], v[146:147], v[152:153]
	v_pk_fma_f32 v[160:161], v[144:145], v[158:159], v[160:161]
	v_pk_fma_f32 v[144:145], v[144:145], v[156:157], v[146:147]
	v_add_f32_e32 v146, v160, v161
	v_cndmask_b32_e64 v160, v162, v163, s[6:7]
	v_cndmask_b32_e64 v161, v164, v165, s[6:7]
	v_cndmask_b32_e64 v162, v163, v162, s[6:7]
	v_cndmask_b32_e64 v163, v165, v164, s[6:7]
	v_add_f32_e32 v144, v144, v145
	v_add_f32_dpp v160, v160, v162 quad_perm:[1,0,3,2] row_mask:0xf bank_mask:0xf bound_ctrl:1
	v_add_f32_dpp v161, v161, v163 quad_perm:[1,0,3,2] row_mask:0xf bank_mask:0xf bound_ctrl:1
	v_add_f32_dpp v145, v146, v146 quad_perm:[1,0,3,2] row_mask:0xf bank_mask:0xf bound_ctrl:1
	v_add_f32_dpp v144, v144, v144 quad_perm:[1,0,3,2] row_mask:0xf bank_mask:0xf bound_ctrl:1
	v_cndmask_b32_e64 v162, v160, v161, s[8:9]
	v_cndmask_b32_e64 v160, v161, v160, s[8:9]
	v_add_f32_dpp v145, v145, v145 quad_perm:[2,3,0,1] row_mask:0xf bank_mask:0xf bound_ctrl:1
	v_add_f32_dpp v146, v144, v144 quad_perm:[2,3,0,1] row_mask:0xf bank_mask:0xf bound_ctrl:1
	v_add_f32_dpp v160, v162, v160 quad_perm:[2,3,0,1] row_mask:0xf bank_mask:0xf bound_ctrl:1
	v_add_f32_dpp v144, v145, v145 row_ror:4 row_mask:0xf bank_mask:0xf bound_ctrl:1
	v_add_f32_dpp v145, v146, v146 row_ror:4 row_mask:0xf bank_mask:0xf bound_ctrl:1
	v_mov_b32_e32 v146, 0
	v_mov_b32_e32 v147, 0
	v_add_f32_dpp v160, v160, v160 row_ror:4 row_mask:0xf bank_mask:0xf bound_ctrl:1
	v_mov_b32_e32 v161, 0
	v_mov_b32_dpp v146, v144 row_ror:8 row_mask:0xf bank_mask:0xf
	v_mov_b32_dpp v147, v145 row_ror:8 row_mask:0xf bank_mask:0xf
	v_mov_b32_dpp v161, v160 row_ror:8 row_mask:0xf bank_mask:0xf
	s_and_saveexec_b64 s[78:79], s[10:11]
	v_add_f32_e32 v160, v160, v161
	ds_write_b32 v245, v160 offset:3328
	s_or_b64 exec, exec, s[78:79]
	v_pk_mul_f32 v[158:159], v[120:121], v[158:159]
	v_pk_mul_f32 v[154:155], v[122:123], v[154:155]
	v_pk_mul_f32 v[120:121], v[120:121], v[156:157]
	v_pk_mul_f32 v[122:123], v[122:123], v[152:153]
	v_pk_fma_f32 v[158:159], v[124:125], v[72:73], v[158:159] op_sel_hi:[1,0,1]
	v_pk_fma_f32 v[154:155], v[126:127], v[72:73], v[154:155] op_sel_hi:[1,0,1]
	v_pk_fma_f32 v[120:121], v[124:125], v[72:73], v[120:121] op_sel:[0,1,0]
	v_pk_fma_f32 v[72:73], v[126:127], v[72:73], v[122:123] op_sel:[0,1,0]
	v_add_f32_e32 v122, v144, v146
	v_add_f32_e32 v124, v145, v147
	v_pk_fma_f32 v[126:127], v[112:113], v[122:123], v[158:159] op_sel_hi:[1,0,1] neg_lo:[1,0,0] neg_hi:[1,0,0]
	v_pk_fma_f32 v[122:123], v[114:115], v[122:123], v[154:155] op_sel_hi:[1,0,1] neg_lo:[1,0,0] neg_hi:[1,0,0]
	v_pk_fma_f32 v[72:73], v[114:115], v[124:125], v[72:73] op_sel_hi:[1,0,1] neg_lo:[1,0,0] neg_hi:[1,0,0]
	s_waitcnt lgkmcnt(12)
	v_pk_mul_f32 v[114:115], v[118:119], v[122:123]
	v_pk_fma_f32 v[112:113], v[112:113], v[124:125], v[120:121] op_sel_hi:[1,0,1] neg_lo:[1,0,0] neg_hi:[1,0,0]
	v_pk_fma_f32 v[114:115], v[116:117], v[126:127], v[114:115]
	v_pk_mul_f32 v[118:119], v[118:119], v[72:73]
	s_nop 0
	v_pk_fma_f32 v[116:117], v[116:117], v[112:113], v[118:119]
	v_add_f32_e32 v118, v114, v115
	v_pk_mul_f32 v[114:115], v[90:91], v[122:123]
	v_pk_mul_f32 v[90:91], v[90:91], v[72:73]
	v_pk_fma_f32 v[114:115], v[88:89], v[126:127], v[114:115]
	v_pk_fma_f32 v[88:89], v[88:89], v[112:113], v[90:91]
	v_add_f32_e32 v114, v114, v115
	v_add_f32_e32 v115, v88, v89
	v_pk_mul_f32 v[72:73], v[78:79], v[72:73]
	v_pk_mul_f32 v[90:91], v[78:79], v[122:123]
	v_pk_fma_f32 v[78:79], v[82:83], v[74:75], v[72:73] op_sel:[0,1,0]
	v_add_f32_dpp v72, v114, v114 quad_perm:[1,0,3,2] row_mask:0xf bank_mask:0xf bound_ctrl:1
	v_add_f32_dpp v73, v115, v115 quad_perm:[1,0,3,2] row_mask:0xf bank_mask:0xf bound_ctrl:1
	v_pk_mul_f32 v[88:89], v[76:77], v[126:127]
	v_add_f32_dpp v72, v72, v72 quad_perm:[2,3,0,1] row_mask:0xf bank_mask:0xf bound_ctrl:1
	v_add_f32_dpp v73, v73, v73 quad_perm:[2,3,0,1] row_mask:0xf bank_mask:0xf bound_ctrl:1
	v_pk_mul_f32 v[76:77], v[76:77], v[112:113]
	v_add_f32_dpp v72, v72, v72 row_ror:4 row_mask:0xf bank_mask:0xf bound_ctrl:1
	v_add_f32_dpp v73, v73, v73 row_ror:4 row_mask:0xf bank_mask:0xf bound_ctrl:1
	v_pk_fma_f32 v[88:89], v[80:81], v[74:75], v[88:89] op_sel_hi:[1,0,1]
	v_pk_fma_f32 v[90:91], v[82:83], v[74:75], v[90:91] op_sel_hi:[1,0,1]
	v_pk_fma_f32 v[80:81], v[80:81], v[74:75], v[76:77] op_sel:[0,1,0]
	v_add_f32_dpp v72, v72, v72 row_ror:8 row_mask:0xf bank_mask:0xf bound_ctrl:1
	v_add_f32_dpp v82, v73, v73 row_ror:8 row_mask:0xf bank_mask:0xf bound_ctrl:1
	v_pk_fma_f32 v[76:77], v[64:65], v[72:73], v[88:89] op_sel_hi:[1,0,1] neg_lo:[1,0,0] neg_hi:[1,0,0]
	v_pk_fma_f32 v[72:73], v[66:67], v[72:73], v[90:91] op_sel_hi:[1,0,1] neg_lo:[1,0,0] neg_hi:[1,0,0]
	v_pk_fma_f32 v[74:75], v[64:65], v[82:83], v[80:81] op_sel_hi:[1,0,1] neg_lo:[1,0,0] neg_hi:[1,0,0]
	v_pk_fma_f32 v[64:65], v[66:67], v[82:83], v[78:79] op_sel_hi:[1,0,1] neg_lo:[1,0,0] neg_hi:[1,0,0]
	s_waitcnt lgkmcnt(11)
	v_pk_mul_f32 v[66:67], v[70:71], v[72:73]
	v_pk_mul_f32 v[70:71], v[70:71], v[64:65]
	v_pk_fma_f32 v[66:67], v[68:69], v[76:77], v[66:67]
	v_pk_fma_f32 v[68:69], v[68:69], v[74:75], v[70:71]
	v_add_f32_e32 v70, v66, v67
	v_add_f32_e32 v71, v68, v69
	v_add_f32_e32 v116, v116, v117
	s_waitcnt lgkmcnt(7)
	v_pk_mul_f32 v[66:67], v[150:151], v[72:73]
	v_pk_mul_f32 v[68:69], v[150:151], v[64:65]
	v_pk_fma_f32 v[66:67], v[148:149], v[76:77], v[66:67]
	v_pk_fma_f32 v[68:69], v[148:149], v[74:75], v[68:69]
	v_cndmask_b32_e64 v78, v118, v116, s[6:7]
	v_cndmask_b32_e64 v79, v70, v71, s[6:7]
	v_cndmask_b32_e64 v80, v116, v118, s[6:7]
	v_cndmask_b32_e64 v70, v71, v70, s[6:7]
	v_add_f32_e32 v66, v66, v67
	v_add_f32_e32 v67, v68, v69
	v_add_f32_dpp v71, v78, v80 quad_perm:[1,0,3,2] row_mask:0xf bank_mask:0xf bound_ctrl:1
	v_add_f32_dpp v70, v79, v70 quad_perm:[1,0,3,2] row_mask:0xf bank_mask:0xf bound_ctrl:1
	v_add_f32_dpp v66, v66, v66 quad_perm:[1,0,3,2] row_mask:0xf bank_mask:0xf bound_ctrl:1
	v_add_f32_dpp v67, v67, v67 quad_perm:[1,0,3,2] row_mask:0xf bank_mask:0xf bound_ctrl:1
	v_cndmask_b32_e64 v78, v71, v70, s[8:9]
	v_cndmask_b32_e64 v70, v70, v71, s[8:9]
	v_add_f32_dpp v66, v66, v66 quad_perm:[2,3,0,1] row_mask:0xf bank_mask:0xf bound_ctrl:1
	v_add_f32_dpp v67, v67, v67 quad_perm:[2,3,0,1] row_mask:0xf bank_mask:0xf bound_ctrl:1
	v_add_f32_dpp v70, v78, v70 quad_perm:[2,3,0,1] row_mask:0xf bank_mask:0xf bound_ctrl:1
	v_add_f32_dpp v66, v66, v66 row_ror:4 row_mask:0xf bank_mask:0xf bound_ctrl:1
	v_add_f32_dpp v67, v67, v67 row_ror:4 row_mask:0xf bank_mask:0xf bound_ctrl:1
	v_mov_b32_e32 v68, 0
	v_mov_b32_e32 v69, 0
	v_add_f32_dpp v70, v70, v70 row_ror:4 row_mask:0xf bank_mask:0xf bound_ctrl:1
	v_mov_b32_e32 v71, 0
	v_mov_b32_dpp v68, v66 row_ror:8 row_mask:0xf bank_mask:0xf
	v_mov_b32_dpp v69, v67 row_ror:8 row_mask:0xf bank_mask:0xf
	v_mov_b32_dpp v71, v70 row_ror:8 row_mask:0xf bank_mask:0xf
	s_and_saveexec_b64 s[78:79], s[10:11]
	v_add_f32_e32 v70, v70, v71
	ds_write_b32 v245, v70 offset:3584
	s_or_b64 exec, exec, s[78:79]
	v_pk_mul_f32 v[70:71], v[136:137], v[76:77]
	v_pk_mul_f32 v[72:73], v[138:139], v[72:73]
	v_pk_mul_f32 v[64:65], v[138:139], v[64:65]
	s_waitcnt lgkmcnt(3)
	v_pk_fma_f32 v[70:71], v[140:141], v[92:93], v[70:71] op_sel_hi:[1,0,1]
	v_pk_fma_f32 v[72:73], v[142:143], v[92:93], v[72:73] op_sel_hi:[1,0,1]
	v_pk_mul_f32 v[74:75], v[136:137], v[74:75]
	v_pk_fma_f32 v[64:65], v[142:143], v[92:93], v[64:65] op_sel:[0,1,0]
	v_add_f32_e32 v66, v66, v68
	v_add_f32_e32 v68, v67, v69
	v_pk_fma_f32 v[74:75], v[140:141], v[92:93], v[74:75] op_sel:[0,1,0]
	v_pk_fma_f32 v[70:71], v[128:129], v[66:67], v[70:71] op_sel_hi:[1,0,1] neg_lo:[1,0,0] neg_hi:[1,0,0]
	v_pk_fma_f32 v[66:67], v[130:131], v[66:67], v[72:73] op_sel_hi:[1,0,1] neg_lo:[1,0,0] neg_hi:[1,0,0]
	v_pk_fma_f32 v[64:65], v[130:131], v[68:69], v[64:65] op_sel_hi:[1,0,1] neg_lo:[1,0,0] neg_hi:[1,0,0]
	v_pk_fma_f32 v[72:73], v[128:129], v[68:69], v[74:75] op_sel_hi:[1,0,1] neg_lo:[1,0,0] neg_hi:[1,0,0]
	s_waitcnt lgkmcnt(1)
	v_pk_mul_f32 v[68:69], v[134:135], v[66:67]
	v_pk_mul_f32 v[74:75], v[134:135], v[64:65]
	v_pk_fma_f32 v[68:69], v[132:133], v[70:71], v[68:69]
	v_pk_fma_f32 v[74:75], v[132:133], v[72:73], v[74:75]
	v_add_f32_e32 v76, v68, v69
	v_add_f32_e32 v77, v74, v75
	v_pk_mul_f32 v[68:69], v[110:111], v[66:67]
	v_pk_mul_f32 v[74:75], v[110:111], v[64:65]
	v_pk_fma_f32 v[68:69], v[108:109], v[70:71], v[68:69]
	v_pk_fma_f32 v[74:75], v[108:109], v[72:73], v[74:75]
	v_add_f32_e32 v78, v68, v69
	v_add_f32_e32 v74, v74, v75
	v_pk_mul_f32 v[68:69], v[100:101], v[70:71]
	v_pk_mul_f32 v[70:71], v[100:101], v[72:73]
	v_add_f32_dpp v72, v78, v78 quad_perm:[1,0,3,2] row_mask:0xf bank_mask:0xf bound_ctrl:1
	v_add_f32_dpp v73, v74, v74 quad_perm:[1,0,3,2] row_mask:0xf bank_mask:0xf bound_ctrl:1
	v_pk_mul_f32 v[66:67], v[102:103], v[66:67]
	v_add_f32_dpp v72, v72, v72 quad_perm:[2,3,0,1] row_mask:0xf bank_mask:0xf bound_ctrl:1
	v_add_f32_dpp v73, v73, v73 quad_perm:[2,3,0,1] row_mask:0xf bank_mask:0xf bound_ctrl:1
	v_pk_mul_f32 v[64:65], v[102:103], v[64:65]
	v_add_f32_dpp v72, v72, v72 row_ror:4 row_mask:0xf bank_mask:0xf bound_ctrl:1
	v_add_f32_dpp v73, v73, v73 row_ror:4 row_mask:0xf bank_mask:0xf bound_ctrl:1
	v_pk_fma_f32 v[66:67], v[106:107], v[94:95], v[66:67] op_sel_hi:[1,0,1]
	v_pk_fma_f32 v[64:65], v[106:107], v[94:95], v[64:65] op_sel:[0,1,0]
	v_add_f32_dpp v72, v72, v72 row_ror:8 row_mask:0xf bank_mask:0xf bound_ctrl:1
	v_add_f32_dpp v74, v73, v73 row_ror:8 row_mask:0xf bank_mask:0xf bound_ctrl:1
	v_pk_fma_f32 v[68:69], v[104:105], v[94:95], v[68:69] op_sel_hi:[1,0,1]
	v_pk_fma_f32 v[70:71], v[104:105], v[94:95], v[70:71] op_sel:[0,1,0]
	v_pk_fma_f32 v[90:91], v[86:87], v[72:73], v[66:67] op_sel_hi:[1,0,1] neg_lo:[1,0,0] neg_hi:[1,0,0]
	v_pk_fma_f32 v[94:95], v[86:87], v[74:75], v[64:65] op_sel_hi:[1,0,1] neg_lo:[1,0,0] neg_hi:[1,0,0]
	v_pk_fma_f32 v[88:89], v[84:85], v[72:73], v[68:69] op_sel_hi:[1,0,1] neg_lo:[1,0,0] neg_hi:[1,0,0]
	v_pk_fma_f32 v[92:93], v[84:85], v[74:75], v[70:71] op_sel_hi:[1,0,1] neg_lo:[1,0,0] neg_hi:[1,0,0]
	s_waitcnt lgkmcnt(0)
	v_pk_mul_f32 v[64:65], v[98:99], v[90:91]
	v_pk_mul_f32 v[66:67], v[98:99], v[94:95]
	v_pk_fma_f32 v[64:65], v[96:97], v[88:89], v[64:65]
	v_pk_fma_f32 v[66:67], v[96:97], v[92:93], v[66:67]
	v_add_f32_e32 v64, v64, v65
	v_add_f32_e32 v65, v66, v67
	v_cndmask_b32_e64 v66, v76, v77, s[6:7]
	v_cndmask_b32_e64 v67, v64, v65, s[6:7]
	v_cndmask_b32_e64 v68, v77, v76, s[6:7]
	v_cndmask_b32_e64 v64, v65, v64, s[6:7]
	s_nop 0
	v_add_f32_dpp v65, v66, v68 quad_perm:[1,0,3,2] row_mask:0xf bank_mask:0xf bound_ctrl:1
	v_add_f32_dpp v64, v67, v64 quad_perm:[1,0,3,2] row_mask:0xf bank_mask:0xf bound_ctrl:1
	v_cndmask_b32_e64 v66, v65, v64, s[8:9]
	v_cndmask_b32_e64 v64, v64, v65, s[8:9]
	v_mov_b32_e32 v65, 0
	s_nop 0
	v_add_f32_dpp v64, v66, v64 quad_perm:[2,3,0,1] row_mask:0xf bank_mask:0xf bound_ctrl:1
	s_nop 1
	v_add_f32_dpp v64, v64, v64 row_ror:4 row_mask:0xf bank_mask:0xf bound_ctrl:1
	s_nop 1
	v_mov_b32_dpp v65, v64 row_ror:8 row_mask:0xf bank_mask:0xf
	s_and_saveexec_b64 s[78:79], s[10:11]
	v_add3_u32 v66, v176, v239, v197
	v_add_f32_e32 v64, v64, v65
	ds_write_b32 v66, v64 offset:3840
	s_or_b64 exec, exec, s[78:79]
	s_setprio 0
	s_ashr_i32 s28, s24, 5
	s_add_i32 s29, s24, 0xffffff00
	s_not_b32 s28, s28
	s_lshr_b32 s29, s29, 5
	s_cmpk_lt_i32 s24, 0x100
	s_cselect_b32 s28, s28, s29
	s_ashr_i32 s29, s28, 31
	s_lshl_b32 s24, s24, 5
	s_lshl_b64 s[28:29], s[28:29], 10
	s_and_b32 s24, s24, 0x3e0
	s_or_b32 s24, s28, s24
	v_mov_b32_e32 v65, s29
	v_or_b32_e32 v64, s24, v192
	v_lshlrev_b64 v[64:65], 8, v[64:65]
	v_lshl_add_u64 v[64:65], v[198:199], 0, v[64:65]
	global_store_dwordx4 v[64:65], v[88:91], off
	global_store_dwordx4 v[64:65], v[92:95], off offset:256

.LBB0_360:
	s_waitcnt vmcnt(1)
	v_mov_b64_e32 v[42:43], v[22:23]
	s_waitcnt vmcnt(0)
	v_mov_b64_e32 v[46:47], v[18:19]
	s_sub_i32 s24, 0x810, s4
	s_and_b32 s47, s27, 1
	v_mov_b64_e32 v[40:41], v[20:21]
	v_mov_b64_e32 v[44:45], v[16:17]
	s_min_i32 s24, s24, 32
	v_lshl_add_u32 v132, s47, 12, v236
	s_setprio 0
	s_cmpk_gt_i32 s4, 0x80f
	v_mov_b32_e32 v131, 0
	s_cbranch_scc1 .LBB0_371
	s_mul_i32 s47, s47, 0xb000
	s_add_i32 s28, s47, 0
	v_lshl_add_u32 v134, v192, 2, s28
	v_add_u32_e32 v72, 0xa000, v134
	v_add_u32_e32 v133, s28, v196
	ds_read2_b64 v[16:19], v72 offset1:16
	ds_read_b128 v[20:23], v133 offset:33024
	ds_read_b128 v[24:27], v133 offset:32768
	ds_read_b128 v[28:31], v133 offset:24832
	ds_read_b128 v[48:51], v133 offset:24576
	ds_read_b128 v[52:55], v133 offset:16640
	ds_read_b128 v[56:59], v133 offset:16384
	ds_read_b128 v[60:63], v133 offset:8448
	ds_read_b128 v[64:67], v133 offset:8192
	ds_read_b128 v[68:71], v133 offset:256
	ds_read_b128 v[112:115], v133
	ds_read2_b64 v[80:83], v72 offset0:32 offset1:48
	ds_read_b128 v[104:107], v133 offset:512
	ds_read_b128 v[84:87], v133 offset:768
	ds_read_b128 v[120:123], v133 offset:8704
	ds_read_b128 v[92:95], v133 offset:8960
	ds_read_b128 v[96:99], v133 offset:16896
	ds_read_b128 v[72:75], v133 offset:17152
	ds_read_b128 v[108:111], v133 offset:25088
	ds_read_b128 v[88:91], v133 offset:25344
	ds_read_b128 v[100:103], v133 offset:33280
	ds_read_b128 v[76:79], v133 offset:33536
	s_waitcnt lgkmcnt(13)
	v_pk_mul_f32 v[116:117], v[202:203], v[66:67]
	v_pk_mul_f32 v[66:67], v[206:207], v[66:67]
	v_pk_fma_f32 v[116:117], v[204:205], v[64:65], v[116:117]
	v_pk_fma_f32 v[64:65], v[208:209], v[64:65], v[66:67]
	v_add_f32_e32 v66, v116, v117
	v_add_f32_e32 v64, v64, v65
	s_waitcnt lgkmcnt(11)
	v_pk_mul_f32 v[116:117], v[206:207], v[114:115]
	v_add_f32_dpp v65, v66, v66 quad_perm:[1,0,3,2] row_mask:0xf bank_mask:0xf bound_ctrl:1
	v_add_f32_dpp v64, v64, v64 quad_perm:[1,0,3,2] row_mask:0xf bank_mask:0xf bound_ctrl:1
	v_pk_fma_f32 v[116:117], v[16:17], v[50:51], v[116:117] op_sel:[1,0,0]
	v_add_f32_dpp v65, v65, v65 quad_perm:[2,3,0,1] row_mask:0xf bank_mask:0xf bound_ctrl:1
	v_add_f32_dpp v64, v64, v64 quad_perm:[2,3,0,1] row_mask:0xf bank_mask:0xf bound_ctrl:1
	s_nop 0
	v_add_f32_dpp v118, v65, v65 row_ror:4 row_mask:0xf bank_mask:0xf bound_ctrl:1
	v_add_f32_dpp v66, v64, v64 row_ror:4 row_mask:0xf bank_mask:0xf bound_ctrl:1
	v_pk_mul_f32 v[64:65], v[208:209], v[112:113]
	v_pk_mul_f32 v[112:113], v[204:205], v[112:113]
	v_pk_fma_f32 v[64:65], v[16:17], v[48:49], v[64:65] op_sel:[1,0,0]
	v_add_f32_dpp v66, v66, v66 row_ror:8 row_mask:0xf bank_mask:0xf bound_ctrl:1
	v_pk_fma_f32 v[48:49], v[16:17], v[48:49], v[112:113] op_sel_hi:[0,1,1]
	v_add_f32_dpp v112, v118, v118 row_ror:8 row_mask:0xf bank_mask:0xf bound_ctrl:1
	v_pk_fma_f32 v[64:65], v[56:57], v[66:67], v[64:65] op_sel_hi:[1,0,1] neg_lo:[1,0,0] neg_hi:[1,0,0]
	v_pk_fma_f32 v[48:49], v[56:57], v[112:113], v[48:49] op_sel_hi:[1,0,1] neg_lo:[1,0,0] neg_hi:[1,0,0]
	v_pk_mul_f32 v[56:57], v[202:203], v[114:115]
	v_pk_fma_f32 v[66:67], v[58:59], v[66:67], v[116:117] op_sel_hi:[1,0,1] neg_lo:[1,0,0] neg_hi:[1,0,0]
	v_pk_fma_f32 v[16:17], v[16:17], v[50:51], v[56:57] op_sel_hi:[0,1,1]
	v_pk_fma_f32 v[16:17], v[58:59], v[112:113], v[16:17] op_sel_hi:[1,0,1] neg_lo:[1,0,0] neg_hi:[1,0,0]
	v_pk_mul_f32 v[116:117], v[26:27], v[66:67]
	v_pk_mul_f32 v[26:27], v[26:27], v[16:17]
	v_pk_fma_f32 v[116:117], v[24:25], v[64:65], v[116:117]
	v_pk_fma_f32 v[24:25], v[24:25], v[48:49], v[26:27]
	v_pk_mul_f32 v[26:27], v[62:63], v[66:67]
	v_add_f32_e32 v131, v24, v25
	v_pk_mul_f32 v[24:25], v[62:63], v[16:17]
	v_pk_fma_f32 v[26:27], v[60:61], v[64:65], v[26:27]
	v_pk_fma_f32 v[24:25], v[60:61], v[48:49], v[24:25]
	v_add_f32_e32 v51, v26, v27
	v_add_f32_e32 v50, v24, v25
	v_pk_mul_f32 v[24:25], v[68:69], v[48:49]
	v_pk_mul_f32 v[26:27], v[68:69], v[64:65]
	v_pk_fma_f32 v[24:25], v[18:19], v[28:29], v[24:25] op_sel_hi:[0,1,1]
	v_pk_mul_f32 v[16:17], v[70:71], v[16:17]
	v_pk_fma_f32 v[26:27], v[18:19], v[28:29], v[26:27] op_sel:[1,0,0]
	v_pk_mul_f32 v[28:29], v[70:71], v[66:67]
	v_pk_fma_f32 v[16:17], v[18:19], v[30:31], v[16:17] op_sel_hi:[0,1,1]
	v_pk_fma_f32 v[18:19], v[18:19], v[30:31], v[28:29] op_sel:[1,0,0]
	v_add_f32_dpp v28, v50, v50 quad_perm:[1,0,3,2] row_mask:0xf bank_mask:0xf bound_ctrl:1
	v_add_f32_dpp v29, v51, v51 quad_perm:[1,0,3,2] row_mask:0xf bank_mask:0xf bound_ctrl:1
	v_add_f32_e32 v130, v116, v117
	v_add_f32_dpp v28, v28, v28 quad_perm:[2,3,0,1] row_mask:0xf bank_mask:0xf bound_ctrl:1
	v_add_f32_dpp v29, v29, v29 quad_perm:[2,3,0,1] row_mask:0xf bank_mask:0xf bound_ctrl:1
	s_nop 0
	v_add_f32_dpp v28, v28, v28 row_ror:4 row_mask:0xf bank_mask:0xf bound_ctrl:1
	v_add_f32_dpp v29, v29, v29 row_ror:4 row_mask:0xf bank_mask:0xf bound_ctrl:1
	s_nop 0
	v_add_f32_dpp v28, v28, v28 row_ror:8 row_mask:0xf bank_mask:0xf bound_ctrl:1
	v_add_f32_dpp v30, v29, v29 row_ror:8 row_mask:0xf bank_mask:0xf bound_ctrl:1
	v_pk_fma_f32 v[114:115], v[54:55], v[28:29], v[16:17] op_sel_hi:[1,0,1] neg_lo:[1,0,0] neg_hi:[1,0,0]
	v_pk_fma_f32 v[112:113], v[54:55], v[30:31], v[18:19] op_sel_hi:[1,0,1] neg_lo:[1,0,0] neg_hi:[1,0,0]
	v_pk_fma_f32 v[118:119], v[52:53], v[28:29], v[24:25] op_sel_hi:[1,0,1] neg_lo:[1,0,0] neg_hi:[1,0,0]
	v_pk_fma_f32 v[116:117], v[52:53], v[30:31], v[26:27] op_sel_hi:[1,0,1] neg_lo:[1,0,0] neg_hi:[1,0,0]
	v_pk_mul_f32 v[16:17], v[22:23], v[114:115]
	v_pk_mul_f32 v[18:19], v[22:23], v[112:113]
	v_pk_fma_f32 v[16:17], v[20:21], v[118:119], v[16:17]
	v_pk_fma_f32 v[18:19], v[20:21], v[116:117], v[18:19]
	v_add_f32_e32 v135, v16, v17
	v_add_f32_e32 v136, v18, v19
	s_cmpk_lt_i32 s4, 0x80c
	s_cselect_b64 s[78:79], -1, 0
	s_and_b64 s[28:29], s[78:79], exec
	s_cselect_b32 s28, 4, 0
	v_lshl_add_u32 v16, s28, 8, v133
	v_lshl_add_u32 v17, s28, 7, v134
	s_or_b32 s28, s28, 1
	v_lshl_add_u32 v56, s28, 8, v133
	ds_read_b128 v[68:71], v16 offset:8192
	ds_read_b128 v[28:31], v16 offset:16384
	ds_read_b128 v[60:63], v16
	ds_read_b128 v[52:55], v16 offset:32768
	ds_read_b128 v[64:67], v16 offset:24576
	ds_read_b64 v[126:127], v17 offset:40960
	ds_read_b128 v[48:51], v56 offset:8192
	ds_read_b128 v[16:19], v56 offset:16384
	ds_read_b128 v[24:27], v56
	ds_read_b128 v[20:23], v56 offset:32768
	v_lshl_add_u32 v124, s28, 7, v134
	ds_read_b128 v[56:59], v56 offset:24576
	ds_read_b64 v[124:125], v124 offset:40960
	s_waitcnt lgkmcnt(14)
	v_pk_mul_f32 v[128:129], v[122:123], v[114:115]
	v_pk_mul_f32 v[122:123], v[122:123], v[112:113]
	v_pk_fma_f32 v[128:129], v[120:121], v[118:119], v[128:129]
	v_pk_fma_f32 v[120:121], v[120:121], v[116:117], v[122:123]
	v_add_f32_e32 v122, v128, v129
	v_cndmask_b32_e64 v128, v131, v130, s[6:7]
	v_cndmask_b32_e64 v129, v135, v136, s[6:7]
	v_cndmask_b32_e64 v130, v130, v131, s[6:7]
	v_cndmask_b32_e64 v131, v136, v135, s[6:7]
	v_add_f32_e32 v120, v120, v121
	v_add_f32_dpp v128, v128, v130 quad_perm:[1,0,3,2] row_mask:0xf bank_mask:0xf bound_ctrl:1
	v_add_f32_dpp v129, v129, v131 quad_perm:[1,0,3,2] row_mask:0xf bank_mask:0xf bound_ctrl:1
	v_add_f32_dpp v121, v122, v122 quad_perm:[1,0,3,2] row_mask:0xf bank_mask:0xf bound_ctrl:1
	v_add_f32_dpp v120, v120, v120 quad_perm:[1,0,3,2] row_mask:0xf bank_mask:0xf bound_ctrl:1
	v_cndmask_b32_e64 v130, v128, v129, s[8:9]
	v_cndmask_b32_e64 v128, v129, v128, s[8:9]
	v_add_f32_dpp v121, v121, v121 quad_perm:[2,3,0,1] row_mask:0xf bank_mask:0xf bound_ctrl:1
	v_add_f32_dpp v122, v120, v120 quad_perm:[2,3,0,1] row_mask:0xf bank_mask:0xf bound_ctrl:1
	v_add_f32_dpp v128, v130, v128 quad_perm:[2,3,0,1] row_mask:0xf bank_mask:0xf bound_ctrl:1
	v_add_f32_dpp v120, v121, v121 row_ror:4 row_mask:0xf bank_mask:0xf bound_ctrl:1
	v_add_f32_dpp v121, v122, v122 row_ror:4 row_mask:0xf bank_mask:0xf bound_ctrl:1
	v_mov_b32_e32 v122, v177
	v_mov_b32_e32 v123, v177
	v_add_f32_dpp v128, v128, v128 row_ror:4 row_mask:0xf bank_mask:0xf bound_ctrl:1
	v_mov_b32_e32 v129, v177
	v_mov_b32_dpp v122, v120 row_ror:8 row_mask:0xf bank_mask:0xf
	v_mov_b32_dpp v123, v121 row_ror:8 row_mask:0xf bank_mask:0xf
	v_mov_b32_dpp v129, v128 row_ror:8 row_mask:0xf bank_mask:0xf
	s_and_saveexec_b64 s[80:81], s[10:11]
	v_add3_u32 v130, v132, v197, v240
	v_add_f32_e32 v128, v128, v129
	ds_write_b32 v130, v128
	s_or_b64 exec, exec, s[80:81]
	v_pk_mul_f32 v[118:119], v[104:105], v[118:119]
	v_pk_mul_f32 v[114:115], v[106:107], v[114:115]
	v_pk_mul_f32 v[104:105], v[104:105], v[116:117]
	v_pk_mul_f32 v[106:107], v[106:107], v[112:113]
	v_pk_fma_f32 v[118:119], v[108:109], v[80:81], v[118:119] op_sel_hi:[1,0,1]
	v_pk_fma_f32 v[114:115], v[110:111], v[80:81], v[114:115] op_sel_hi:[1,0,1]
	v_pk_fma_f32 v[104:105], v[108:109], v[80:81], v[104:105] op_sel:[0,1,0]
	v_pk_fma_f32 v[80:81], v[110:111], v[80:81], v[106:107] op_sel:[0,1,0]
	v_add_f32_e32 v106, v120, v122
	v_add_f32_e32 v108, v121, v123
	v_pk_fma_f32 v[110:111], v[96:97], v[106:107], v[118:119] op_sel_hi:[1,0,1] neg_lo:[1,0,0] neg_hi:[1,0,0]
	v_pk_fma_f32 v[106:107], v[98:99], v[106:107], v[114:115] op_sel_hi:[1,0,1] neg_lo:[1,0,0] neg_hi:[1,0,0]
	v_pk_fma_f32 v[80:81], v[98:99], v[108:109], v[80:81] op_sel_hi:[1,0,1] neg_lo:[1,0,0] neg_hi:[1,0,0]
	v_pk_fma_f32 v[96:97], v[96:97], v[108:109], v[104:105] op_sel_hi:[1,0,1] neg_lo:[1,0,0] neg_hi:[1,0,0]
	s_waitcnt lgkmcnt(13)
	v_pk_mul_f32 v[98:99], v[102:103], v[106:107]
	v_pk_mul_f32 v[102:103], v[102:103], v[80:81]
	v_pk_fma_f32 v[98:99], v[100:101], v[110:111], v[98:99]
	v_pk_fma_f32 v[100:101], v[100:101], v[96:97], v[102:103]
	v_mov_b32_e32 v103, v98
	v_mov_b32_e32 v102, v100
	v_mov_b32_e32 v98, v101
	v_pk_add_f32 v[128:129], v[102:103], v[98:99]
	v_pk_mul_f32 v[98:99], v[94:95], v[106:107]
	v_pk_mul_f32 v[94:95], v[94:95], v[80:81]
	v_pk_fma_f32 v[98:99], v[92:93], v[110:111], v[98:99]
	v_pk_fma_f32 v[92:93], v[92:93], v[96:97], v[94:95]
	v_add_f32_e32 v98, v98, v99
	v_add_f32_e32 v99, v92, v93
	v_pk_mul_f32 v[92:93], v[84:85], v[110:111]
	v_pk_mul_f32 v[94:95], v[86:87], v[106:107]
	v_pk_mul_f32 v[84:85], v[84:85], v[96:97]
	v_pk_mul_f32 v[80:81], v[86:87], v[80:81]
	v_pk_fma_f32 v[92:93], v[88:89], v[82:83], v[92:93] op_sel_hi:[1,0,1]
	v_pk_fma_f32 v[94:95], v[90:91], v[82:83], v[94:95] op_sel_hi:[1,0,1]
	v_pk_fma_f32 v[84:85], v[88:89], v[82:83], v[84:85] op_sel:[0,1,0]
	v_pk_fma_f32 v[80:81], v[90:91], v[82:83], v[80:81] op_sel:[0,1,0]
	v_add_f32_dpp v82, v98, v98 quad_perm:[1,0,3,2] row_mask:0xf bank_mask:0xf bound_ctrl:1
	v_add_f32_dpp v83, v99, v99 quad_perm:[1,0,3,2] row_mask:0xf bank_mask:0xf bound_ctrl:1
	s_nop 0
	v_add_f32_dpp v82, v82, v82 quad_perm:[2,3,0,1] row_mask:0xf bank_mask:0xf bound_ctrl:1
	v_add_f32_dpp v83, v83, v83 quad_perm:[2,3,0,1] row_mask:0xf bank_mask:0xf bound_ctrl:1
	s_nop 0
	v_add_f32_dpp v82, v82, v82 row_ror:4 row_mask:0xf bank_mask:0xf bound_ctrl:1
	v_add_f32_dpp v83, v83, v83 row_ror:4 row_mask:0xf bank_mask:0xf bound_ctrl:1
	s_nop 0
	v_add_f32_dpp v82, v82, v82 row_ror:8 row_mask:0xf bank_mask:0xf bound_ctrl:1
	v_add_f32_dpp v86, v83, v83 row_ror:8 row_mask:0xf bank_mask:0xf bound_ctrl:1
	v_pk_fma_f32 v[90:91], v[74:75], v[82:83], v[94:95] op_sel_hi:[1,0,1] neg_lo:[1,0,0] neg_hi:[1,0,0]
	v_pk_fma_f32 v[94:95], v[74:75], v[86:87], v[80:81] op_sel_hi:[1,0,1] neg_lo:[1,0,0] neg_hi:[1,0,0]
	v_pk_fma_f32 v[88:89], v[72:73], v[82:83], v[92:93] op_sel_hi:[1,0,1] neg_lo:[1,0,0] neg_hi:[1,0,0]
	v_pk_fma_f32 v[92:93], v[72:73], v[86:87], v[84:85] op_sel_hi:[1,0,1] neg_lo:[1,0,0] neg_hi:[1,0,0]
	s_waitcnt lgkmcnt(12)
	v_pk_mul_f32 v[72:73], v[78:79], v[90:91]
	v_pk_mul_f32 v[74:75], v[78:79], v[94:95]
	v_pk_fma_f32 v[72:73], v[76:77], v[88:89], v[72:73]
	v_pk_fma_f32 v[74:75], v[76:77], v[92:93], v[74:75]
	v_mov_b32_e32 v77, v72
	v_mov_b32_e32 v76, v74
	v_mov_b32_e32 v72, v75
	v_pk_add_f32 v[130:131], v[76:77], v[72:73]
	s_andn2_b64 vcc, exec, s[78:79]
	s_cbranch_vccnz .LBB0_372
	v_cndmask_b32_e64 v72, 0, 1, s[72:73]
	s_mov_b32 s28, 0xb000
	v_lshl_or_b32 v135, v72, 12, v241
	v_add_u32_e32 v135, 0x16100, v135
	v_mul_lo_u32 v72, v72, s28
	v_add_u32_e32 v136, v242, v72
	v_or_b32_e32 v137, v243, v72
	s_mov_b32 s47, 4
	.p2alignl 6, 3212836864
